# K-loop LDS-DMA loads use SGPR base + 32-bit voffset in P1/P6/P7/P8; P1 epilogue SGPR base + sc0 sc1 stores; P7 rowsq loads hoisted
# speedup vs baseline: 1.0137x; 1.0095x over previous
; #define PG8_STAGE(bufoff, gbase, voff) do { _Pragma("unroll") for (int _i = 0; _i < 2; ++_i) \
;         __builtin_amdgcn_global_load_lds((const unsigned*)((const char*)(gbase) + (voff)[_i]), (PG8_LAS unsigned*)(lds + (bufoff) + ldsw + _i * 8192), 16, 0, 0); } while (0)
; #define PG8_WAIT_V(n) asm volatile("s_waitcnt vmcnt(" #n ")" ::: "memory")
; #define PG8_BAR __builtin_amdgcn_s_barrier()
; template <class Epi, class Sched, bool ALIGN_EPI = false, bool SP2 = false>
; __device__ __forceinline__ void gemm_phase(PG8_LAS unsigned char* lds, const Gemm g, const Sched& S, const Epi& E) {
;     const int tid = threadIdx.x, wid = __builtin_amdgcn_readfirstlane(tid >> 6), lane = tid & 63, wr = wid >> 2, wc = wid & 3, fr = lane & 15, fq = lane >> 4;
;     const int K = g.K, nt = K / BK;
;     unsigned voffA[2], voffB[2];
; #pragma unroll
;     for (int i = 0; i < 2; ++i) { int R, C; stage_rc(tid * 16 + i * 8192, R, C); const int Rb = Epi::PERM ? ((R & ~31) + perm32(R & 31)) : R;
;         voffA[i] = (unsigned)(R * K + C) * 2u; voffB[i] = (unsigned)(Rb * K + C) * 2u; }
;     const size_t kstep = (size_t)(BK * 2);
;     const size_t hstep = (size_t)HALF * K * 2;
;     const size_t tstep = 2 * hstep;
;     const unsigned ldsw = (unsigned)wid * 1024u;
;     const int aoff = lds_byte(wr * 64 + fr, fq * 8), boff = lds_byte(wc * 32 + fr, fq * 8);
;     ...
;         PG8_STAGE(PG8_SB(0, 0), cB, voffB); PG8_STAGE(PG8_SB(0, 1), cB + hstep, voffB); PG8_STAGE(PG8_SA(0, 0), cA, voffA); PG8_STAGE(PG8_SA(0, 1), cA + hstep, voffA);
;         if (wr == 1) PG8_BAR;
;         PG8_WAIT_V(2); PG8_BAR;
;         PG8_STAGE(PG8_SB(1, 0), cB + kstep, voffB); PG8_STAGE(PG8_SA(1, 0), cA + kstep, voffA); PG8_STAGE(PG8_SB(1, 1), cB + hstep + kstep, voffB);
;         PG8_WAIT_V(6); PG8_BAR;
.LBB0_55:
	s_lshl_b32 s8, s8, 5
	s_and_b32 s14, s8, 0x60
	s_mov_b64 s[8:9], 0x80
	s_add_i32 m0, s47, 0x18000
	v_lshl_add_u64 v[6:7], v[6:7], 0, s[8:9]
	s_lshl_b32 s11, s10, 13
	s_lshl_b32 s15, s14, 7
	s_waitcnt vmcnt(2)
	s_barrier
	global_load_lds_dwordx4 v[6:7], off
	v_lshl_add_u64 v[4:5], v[4:5], 0, s[8:9]
	s_add_i32 m0, s47, 0x1a000
	s_add_i32 s77, s47, 0x8000
	s_add_i32 s78, s47, 0xa000
	global_load_lds_dwordx4 v[4:5], off
	v_lshl_add_u64 v[0:1], v[0:1], 0, s[8:9]
	s_mov_b32 m0, s77
	s_add_u32 s12, s68, 0x80080
	global_load_lds_dwordx4 v[0:1], off
	v_lshl_add_u64 v[0:1], v[2:3], 0, s[8:9]
	s_mov_b32 m0, s78
	s_addc_u32 s13, s69, 0
	global_load_lds_dwordx4 v[0:1], off
	s_add_i32 m0, s47, 0x1c000
	v_lshl_add_u64 v[0:1], s[12:13], 0, v[132:133]
	global_load_lds_dwordx4 v[0:1], off
	v_lshl_add_u64 v[0:1], s[12:13], 0, v[128:129]
	s_add_i32 m0, s47, 0x1e000
	s_sext_i32_i16 s86, s0
	global_load_lds_dwordx4 v[0:1], off
	v_and_b32_e32 v0, 15, v220
	v_lshlrev_b32_e32 v1, 1, v11
	v_lshlrev_b32_e32 v2, 2, v220
	v_lshlrev_b32_e32 v3, 6, v220
	s_movk_i32 s0, 0x3c0
	v_lshl_or_b32 v148, s10, 6, v0
	v_lshl_or_b32 v0, v0, 6, v1
	v_and_b32_e32 v2, 32, v2
	v_and_or_b32 v1, v3, s0, v1
	v_bitop3_b32 v149, s15, v1, v2 bitop3:0xf6
	v_lshlrev_b32_e32 v1, 9, v220
	v_bitop3_b32 v0, v0, s11, v2 bitop3:0xde
	v_and_b32_e32 v1, 0x70000, v1
	v_lshlrev_b32_e32 v2, 12, v12
	v_or3_b32 v1, v9, v1, v2
	v_add_u32_e32 v138, v1, v10
	v_lshlrev_b32_e32 v1, 5, v8
	s_waitcnt vmcnt(6)
	s_cmpk_lt_u32 s1, 0x100
	v_and_b32_e32 v1, 0xf0000, v1
	s_cselect_b64 s[10:11], -1, 0
	v_or3_b32 v1, v9, v1, v2
	s_add_i32 s80, 0, 0x10000
	s_add_i32 s81, 0, 0x14000
	s_waitcnt lgkmcnt(0)
	s_ashr_i32 s79, s33, 31
	v_or_b32_e32 v150, s14, v11
	v_lshlrev_b32_e32 v230, 11, v148
	v_lshl_add_u32 v230, v150, 1, v230
	v_mov_b32_e32 v139, v137
	v_add_u32_e32 v140, v1, v10
	v_mov_b32_e32 v141, v137
	v_mov_b64_e32 v[142:143], 0x1600
	v_mov_b64_e32 v[144:145], 0x15ff
	v_add_u32_e32 v151, s80, v149
	v_add_u32_e32 v152, s81, v149
	v_add_u32_e32 v153, 0, v0
	s_mov_b64 s[12:13], 0x40000
	s_mov_b32 s82, 0x40000
	s_mov_b64 s[14:15], 0x48000
	s_mov_b32 s83, 0x48000
	s_mov_b64 s[16:17], 0x50000
	s_mov_b32 s84, 0x50000
	s_mov_b64 s[18:19], 0x58000
	s_mov_b32 s85, 0x58000
	s_barrier
	s_waitcnt vmcnt(0)
	s_branch .LBB0_58

; #define PG8_STAGE(bufoff, gbase, voff) do { _Pragma("unroll") for (int _i = 0; _i < 2; ++_i) \
;         __builtin_amdgcn_global_load_lds((const unsigned*)((const char*)(gbase) + (voff)[_i]), (PG8_LAS unsigned*)(lds + (bufoff) + ldsw + _i * 8192), 16, 0, 0); } while (0)
; #define PG8_LDA(dst, b, h) do { _Pragma("unroll") for (int m = 0; m < 4; ++m) _Pragma("unroll") for (int k = 0; k < 2; ++k) dst[m][k] = *(const PG8_LAS bf16x8*)(lds + PG8_SA(b, h) + aoff + m * 2048 + k * 1024); } while (0)
; #define PG8_LDB(dst, b, h) do { _Pragma("unroll") for (int n = 0; n < 2; ++n) _Pragma("unroll") for (int k = 0; k < 2; ++k) dst[n][k] = *(const PG8_LAS bf16x8*)(lds + PG8_SB(b, h) + boff + n * 2048 + k * 1024); } while (0)
; #define PG8_MMA(ai, bj, At, Bt) do { __builtin_amdgcn_s_setprio(1); _Pragma("unroll") for (int m = 0; m < 4; ++m) _Pragma("unroll") for (int n = 0; n < 2; ++n) _Pragma("unroll") for (int k = 0; k < 2; ++k) \
;         acc[ai][bj][m][n] = __builtin_amdgcn_mfma_f32_16x16x32_bf16(Bt[n][k], At[m][k], acc[ai][bj][m][n], 0, 0, 0); __builtin_amdgcn_s_setprio(0); } while (0)
; #define PG8_BAR __builtin_amdgcn_s_barrier()
; template <class Epi, class Sched, bool ALIGN_EPI = false, bool SP2 = false>
; __device__ __forceinline__ void gemm_phase(PG8_LAS unsigned char* lds, const Gemm g, const Sched& S, const Epi& E) {
;     ...
;         for (int t = 0; t < nt; t += 2) {
;             const bool last = (t == nt - 2);
;             const char* a1 = cA + (size_t)(t + 1) * kstep;
;             const char* a2 = last ? nA : cA + (size_t)(t + 2) * kstep; const char* b2 = last ? nB : cB + (size_t)(t + 2) * kstep;
;             const char* a3 = a2 + kstep; const char* b3 = b2 + kstep;
;             if (last && has_next) S.a_ready(nxt);
;             if constexpr (Epi::MID) { if (t == (nt >> 1)) E.mid(acc, cur, wr, wc, fr, fq); }
;             if constexpr (SP2) {
;             PG8_LDB(B0, 0, 0); PG8_LDB(B1, 0, 1); PG8_SCHED; PG8_LDA(At, 0, 0); PG8_STAGE(PG8_SA(1, 1), a1 + hstep, voffA);
;             PG8_WAIT_V(8); PG8_WAIT_L(0); PG8_BAR; PG8_MMA(0, 0, At, B0); PG8_MMA(0, 1, At, B1); PG8_BAR; PG8_SCHED;
;             PG8_LDA(At, 0, 1); PG8_STAGE(PG8_SB(0, 0), b2, voffB); PG8_STAGE(PG8_SB(0, 1), b2 + hstep, voffB); PG8_STAGE(PG8_SA(0, 0), a2, voffA);
;             PG8_WAIT_V(8); PG8_WAIT_L(0); PG8_BAR; PG8_MMA(1, 0, At, B0); PG8_MMA(1, 1, At, B1); PG8_BAR; PG8_SCHED;
.LBB0_61:
	ds_read_b128 v[154:157], v151
	ds_read_b128 v[158:161], v151 offset:1024
	ds_read_b128 v[162:165], v151 offset:2048
	ds_read_b128 v[166:169], v151 offset:3072
	ds_read_b128 v[170:173], v152
	ds_read_b128 v[174:177], v152 offset:1024
	ds_read_b128 v[178:181], v152 offset:2048
	ds_read_b128 v[182:185], v152 offset:3072
	s_add_u32 s52, s54, 0xfff80080
	s_addc_u32 s53, s55, -1
	s_cmp_eq_u32 s91, 28
	s_cselect_b32 s71, s23, s53
	s_cselect_b32 s70, s87, s52
	s_cselect_b32 s69, s21, s90
	s_cselect_b32 s68, s88, s89
	s_add_i32 m0, s47, 0xc000
	ds_read_b128 v[186:189], v153
	ds_read_b128 v[190:193], v153 offset:1024
	ds_read_b128 v[194:197], v153 offset:2048
	ds_read_b128 v[198:201], v153 offset:3072
	ds_read_b128 v[202:205], v153 offset:4096
	ds_read_b128 v[206:209], v153 offset:5120
	ds_read_b128 v[210:213], v153 offset:6144
	ds_read_b128 v[214:217], v153 offset:7168
	global_load_lds_dwordx4 v138, s[54:55]
	s_add_i32 m0, s47, 0xe000
	s_nop 0
	global_load_lds_dwordx4 v140, s[54:55]
	s_waitcnt vmcnt(8)
	s_waitcnt lgkmcnt(0)
	s_barrier
	s_setprio 1
	s_waitcnt lgkmcnt(0)
	v_mfma_f32_16x16x32_bf16 v[124:127], v[154:157], v[186:189], v[124:127]
	v_mfma_f32_16x16x32_bf16 v[120:123], v[162:165], v[186:189], v[120:123]
	v_mfma_f32_16x16x32_bf16 v[116:119], v[154:157], v[194:197], v[116:119]
	v_mfma_f32_16x16x32_bf16 v[108:111], v[162:165], v[194:197], v[108:111]
	v_mfma_f32_16x16x32_bf16 v[100:103], v[154:157], v[202:205], v[100:103]
	v_mfma_f32_16x16x32_bf16 v[92:95], v[162:165], v[202:205], v[92:95]
	v_mfma_f32_16x16x32_bf16 v[84:87], v[154:157], v[210:213], v[84:87]
	v_mfma_f32_16x16x32_bf16 v[76:79], v[162:165], v[210:213], v[76:79]
	v_mfma_f32_16x16x32_bf16 v[124:127], v[158:161], v[190:193], v[124:127]
	v_mfma_f32_16x16x32_bf16 v[120:123], v[166:169], v[190:193], v[120:123]
	v_mfma_f32_16x16x32_bf16 v[116:119], v[158:161], v[198:201], v[116:119]
	v_mfma_f32_16x16x32_bf16 v[108:111], v[166:169], v[198:201], v[108:111]
	v_mfma_f32_16x16x32_bf16 v[100:103], v[158:161], v[206:209], v[100:103]
	v_mfma_f32_16x16x32_bf16 v[92:95], v[166:169], v[206:209], v[92:95]
	v_mfma_f32_16x16x32_bf16 v[84:87], v[158:161], v[214:217], v[84:87]
	v_mfma_f32_16x16x32_bf16 v[76:79], v[166:169], v[214:217], v[76:79]
	s_setprio 0
	s_setprio 1
	v_mfma_f32_16x16x32_bf16 v[112:115], v[170:173], v[186:189], v[112:115]
	v_mfma_f32_16x16x32_bf16 v[104:107], v[178:181], v[186:189], v[104:107]
	v_mfma_f32_16x16x32_bf16 v[96:99], v[170:173], v[194:197], v[96:99]
	v_mfma_f32_16x16x32_bf16 v[88:91], v[178:181], v[194:197], v[88:91]
	v_mfma_f32_16x16x32_bf16 v[80:83], v[170:173], v[202:205], v[80:83]
	v_mfma_f32_16x16x32_bf16 v[72:75], v[178:181], v[202:205], v[72:75]
	v_mfma_f32_16x16x32_bf16 v[68:71], v[170:173], v[210:213], v[68:71]
	v_mfma_f32_16x16x32_bf16 v[64:67], v[178:181], v[210:213], v[64:67]
	v_mfma_f32_16x16x32_bf16 v[112:115], v[174:177], v[190:193], v[112:115]
	v_mfma_f32_16x16x32_bf16 v[104:107], v[182:185], v[190:193], v[104:107]
	v_mfma_f32_16x16x32_bf16 v[96:99], v[174:177], v[198:201], v[96:99]
	v_mfma_f32_16x16x32_bf16 v[88:91], v[182:185], v[198:201], v[88:91]
	v_mfma_f32_16x16x32_bf16 v[80:83], v[174:177], v[206:209], v[80:83]
	v_mfma_f32_16x16x32_bf16 v[72:75], v[182:185], v[206:209], v[72:75]
	v_mfma_f32_16x16x32_bf16 v[68:71], v[174:177], v[214:217], v[68:71]
	v_mfma_f32_16x16x32_bf16 v[64:67], v[182:185], v[214:217], v[64:67]
	s_setprio 0
	s_barrier
	s_add_i32 s52, s80, s3
	s_mov_b32 m0, s52
	ds_read_b128 v[186:189], v153 offset:16384
	ds_read_b128 v[190:193], v153 offset:17408
	ds_read_b128 v[194:197], v153 offset:18432
	ds_read_b128 v[198:201], v153 offset:19456
	ds_read_b128 v[202:205], v153 offset:20480
	ds_read_b128 v[206:209], v153 offset:21504
	ds_read_b128 v[210:213], v153 offset:22528
	ds_read_b128 v[214:217], v153 offset:23552
	global_load_lds_dwordx4 v132, s[68:69]
	s_add_i32 m0, s52, 0x2000
	s_add_u32 s92, s68, 0x80000
	s_addc_u32 s93, s69, 0
	s_add_i32 s52, s81, s3
	global_load_lds_dwordx4 v128, s[68:69]
	s_mov_b32 m0, s52
	s_nop 0
	global_load_lds_dwordx4 v132, s[92:93]
	s_add_i32 m0, s52, 0x2000
	s_nop 0
	global_load_lds_dwordx4 v128, s[92:93]
	s_mov_b32 m0, s47
	s_nop 0
	global_load_lds_dwordx4 v134, s[70:71]
	s_mov_b32 m0, s73
	s_nop 0
	global_load_lds_dwordx4 v130, s[70:71]
	s_waitcnt vmcnt(8)
	s_waitcnt lgkmcnt(0)
	s_barrier
	s_setprio 1
	s_waitcnt lgkmcnt(0)
	v_mfma_f32_16x16x32_bf16 v[60:63], v[154:157], v[186:189], v[60:63]
	v_mfma_f32_16x16x32_bf16 v[56:59], v[162:165], v[186:189], v[56:59]
	v_mfma_f32_16x16x32_bf16 v[52:55], v[154:157], v[194:197], v[52:55]
	v_mfma_f32_16x16x32_bf16 v[44:47], v[162:165], v[194:197], v[44:47]
	v_mfma_f32_16x16x32_bf16 v[36:39], v[154:157], v[202:205], v[36:39]
	v_mfma_f32_16x16x32_bf16 v[28:31], v[162:165], v[202:205], v[28:31]
	v_mfma_f32_16x16x32_bf16 v[20:23], v[154:157], v[210:213], v[20:23]
	v_mfma_f32_16x16x32_bf16 v[12:15], v[162:165], v[210:213], v[12:15]
	v_mfma_f32_16x16x32_bf16 v[60:63], v[158:161], v[190:193], v[60:63]
	v_mfma_f32_16x16x32_bf16 v[56:59], v[166:169], v[190:193], v[56:59]
	v_mfma_f32_16x16x32_bf16 v[52:55], v[158:161], v[198:201], v[52:55]
	v_mfma_f32_16x16x32_bf16 v[44:47], v[166:169], v[198:201], v[44:47]
	v_mfma_f32_16x16x32_bf16 v[36:39], v[158:161], v[206:209], v[36:39]
	v_mfma_f32_16x16x32_bf16 v[28:31], v[166:169], v[206:209], v[28:31]
	v_mfma_f32_16x16x32_bf16 v[20:23], v[158:161], v[214:217], v[20:23]
	v_mfma_f32_16x16x32_bf16 v[12:15], v[166:169], v[214:217], v[12:15]
	s_setprio 0
	s_setprio 1
	v_mfma_f32_16x16x32_bf16 v[48:51], v[170:173], v[186:189], v[48:51]
	v_mfma_f32_16x16x32_bf16 v[40:43], v[178:181], v[186:189], v[40:43]
	v_mfma_f32_16x16x32_bf16 v[32:35], v[170:173], v[194:197], v[32:35]
	v_mfma_f32_16x16x32_bf16 v[24:27], v[178:181], v[194:197], v[24:27]
	v_mfma_f32_16x16x32_bf16 v[16:19], v[170:173], v[202:205], v[16:19]
	v_mfma_f32_16x16x32_bf16 v[8:11], v[178:181], v[202:205], v[8:11]
	v_mfma_f32_16x16x32_bf16 v[4:7], v[170:173], v[210:213], v[4:7]
	v_mfma_f32_16x16x32_bf16 v[0:3], v[178:181], v[210:213], v[0:3]
	v_mfma_f32_16x16x32_bf16 v[48:51], v[174:177], v[190:193], v[48:51]
	v_mfma_f32_16x16x32_bf16 v[40:43], v[182:185], v[190:193], v[40:43]
	v_mfma_f32_16x16x32_bf16 v[32:35], v[174:177], v[198:201], v[32:35]
	v_mfma_f32_16x16x32_bf16 v[24:27], v[182:185], v[198:201], v[24:27]
	v_mfma_f32_16x16x32_bf16 v[16:19], v[174:177], v[206:209], v[16:19]
	v_mfma_f32_16x16x32_bf16 v[8:11], v[182:185], v[206:209], v[8:11]
	v_mfma_f32_16x16x32_bf16 v[4:7], v[174:177], v[214:217], v[4:7]
	v_mfma_f32_16x16x32_bf16 v[0:3], v[182:185], v[214:217], v[0:3]
	s_setprio 0
	s_barrier
; #define PG8_STAGE(bufoff, gbase, voff) do { _Pragma("unroll") for (int _i = 0; _i < 2; ++_i) \
;         __builtin_amdgcn_global_load_lds((const unsigned*)((const char*)(gbase) + (voff)[_i]), (PG8_LAS unsigned*)(lds + (bufoff) + ldsw + _i * 8192), 16, 0, 0); } while (0)
; #define PG8_LDA(dst, b, h) do { _Pragma("unroll") for (int m = 0; m < 4; ++m) _Pragma("unroll") for (int k = 0; k < 2; ++k) dst[m][k] = *(const PG8_LAS bf16x8*)(lds + PG8_SA(b, h) + aoff + m * 2048 + k * 1024); } while (0)
; #define PG8_LDB(dst, b, h) do { _Pragma("unroll") for (int n = 0; n < 2; ++n) _Pragma("unroll") for (int k = 0; k < 2; ++k) dst[n][k] = *(const PG8_LAS bf16x8*)(lds + PG8_SB(b, h) + boff + n * 2048 + k * 1024); } while (0)
; #define PG8_MMA(ai, bj, At, Bt) do { __builtin_amdgcn_s_setprio(1); _Pragma("unroll") for (int m = 0; m < 4; ++m) _Pragma("unroll") for (int n = 0; n < 2; ++n) _Pragma("unroll") for (int k = 0; k < 2; ++k) \
;         acc[ai][bj][m][n] = __builtin_amdgcn_mfma_f32_16x16x32_bf16(Bt[n][k], At[m][k], acc[ai][bj][m][n], 0, 0, 0); __builtin_amdgcn_s_setprio(0); } while (0)
; #define PG8_WAIT_V(n) asm volatile("s_waitcnt vmcnt(" #n ")" ::: "memory")
; #define PG8_WAIT_L(n) asm volatile("s_waitcnt lgkmcnt(" #n ")" ::: "memory")
; #define PG8_BAR __builtin_amdgcn_s_barrier()
; template <class Epi, class Sched, bool ALIGN_EPI = false, bool SP2 = false>
; __device__ __forceinline__ void gemm_phase(PG8_LAS unsigned char* lds, const Gemm g, const Sched& S, const Epi& E) {
;     ...
;         for (int t = 0; t < nt; t += 2) {
;             const bool last = (t == nt - 2);
;             const char* a1 = cA + (size_t)(t + 1) * kstep;
;             const char* a2 = last ? nA : cA + (size_t)(t + 2) * kstep; const char* b2 = last ? nB : cB + (size_t)(t + 2) * kstep;
;             const char* a3 = a2 + kstep; const char* b3 = b2 + kstep;
;     ...
;             PG8_LDB(B0, 1, 0); PG8_LDB(B1, 1, 1); PG8_SCHED; PG8_LDA(At, 1, 0); PG8_STAGE(PG8_SA(0, 1), a2 + hstep, voffA);
;             PG8_WAIT_V(8); PG8_WAIT_L(0); PG8_BAR; PG8_MMA(0, 0, At, B0); PG8_MMA(0, 1, At, B1); PG8_BAR; PG8_SCHED;
;             PG8_LDA(At, 1, 1); PG8_STAGE(PG8_SB(1, 0), b3, voffB); PG8_STAGE(PG8_SB(1, 1), b3 + hstep, voffB); PG8_STAGE(PG8_SA(1, 0), a3, voffA);
;             PG8_WAIT_V(8); PG8_WAIT_L(0); PG8_BAR; PG8_MMA(1, 0, At, B0); PG8_MMA(1, 1, At, B1); PG8_BAR; PG8_SCHED;
	s_add_i32 s52, 0, 0x18000
	v_add_u32_e32 v136, s52, v149
	s_add_i32 s53, 0, 0x1c000
	ds_read_b128 v[154:157], v136
	ds_read_b128 v[158:161], v136 offset:1024
	ds_read_b128 v[162:165], v136 offset:2048
	ds_read_b128 v[166:169], v136 offset:3072
	v_add_u32_e32 v136, s53, v149
	ds_read_b128 v[170:173], v136
	ds_read_b128 v[174:177], v136 offset:1024
	ds_read_b128 v[178:181], v136 offset:2048
	ds_read_b128 v[182:185], v136 offset:3072
	s_add_u32 s70, s70, 0x80000
	s_addc_u32 s71, s71, 0
	s_mov_b32 m0, s74
	ds_read_b128 v[186:189], v153 offset:32768
	ds_read_b128 v[190:193], v153 offset:33792
	ds_read_b128 v[194:197], v153 offset:34816
	ds_read_b128 v[198:201], v153 offset:35840
	ds_read_b128 v[202:205], v153 offset:36864
	ds_read_b128 v[206:209], v153 offset:37888
	ds_read_b128 v[210:213], v153 offset:38912
	ds_read_b128 v[214:217], v153 offset:39936
	global_load_lds_dwordx4 v134, s[70:71]
	s_mov_b32 m0, s75
	s_nop 0
	global_load_lds_dwordx4 v130, s[70:71]
	s_waitcnt vmcnt(8)
	s_waitcnt lgkmcnt(0)
	s_barrier
	s_setprio 1
	s_waitcnt lgkmcnt(0)
	v_mfma_f32_16x16x32_bf16 v[124:127], v[154:157], v[186:189], v[124:127]
	v_mfma_f32_16x16x32_bf16 v[120:123], v[162:165], v[186:189], v[120:123]
	v_mfma_f32_16x16x32_bf16 v[116:119], v[154:157], v[194:197], v[116:119]
	v_mfma_f32_16x16x32_bf16 v[108:111], v[162:165], v[194:197], v[108:111]
	v_mfma_f32_16x16x32_bf16 v[100:103], v[154:157], v[202:205], v[100:103]
	v_mfma_f32_16x16x32_bf16 v[92:95], v[162:165], v[202:205], v[92:95]
	v_mfma_f32_16x16x32_bf16 v[84:87], v[154:157], v[210:213], v[84:87]
	v_mfma_f32_16x16x32_bf16 v[76:79], v[162:165], v[210:213], v[76:79]
	v_mfma_f32_16x16x32_bf16 v[124:127], v[158:161], v[190:193], v[124:127]
	v_mfma_f32_16x16x32_bf16 v[120:123], v[166:169], v[190:193], v[120:123]
	v_mfma_f32_16x16x32_bf16 v[116:119], v[158:161], v[198:201], v[116:119]
	v_mfma_f32_16x16x32_bf16 v[108:111], v[166:169], v[198:201], v[108:111]
	v_mfma_f32_16x16x32_bf16 v[100:103], v[158:161], v[206:209], v[100:103]
	v_mfma_f32_16x16x32_bf16 v[92:95], v[166:169], v[206:209], v[92:95]
	v_mfma_f32_16x16x32_bf16 v[84:87], v[158:161], v[214:217], v[84:87]
	v_mfma_f32_16x16x32_bf16 v[76:79], v[166:169], v[214:217], v[76:79]
	s_setprio 0
	s_setprio 1
	v_mfma_f32_16x16x32_bf16 v[112:115], v[170:173], v[186:189], v[112:115]
	v_mfma_f32_16x16x32_bf16 v[104:107], v[178:181], v[186:189], v[104:107]
	v_mfma_f32_16x16x32_bf16 v[96:99], v[170:173], v[194:197], v[96:99]
	v_mfma_f32_16x16x32_bf16 v[88:91], v[178:181], v[194:197], v[88:91]
	v_mfma_f32_16x16x32_bf16 v[80:83], v[170:173], v[202:205], v[80:83]
	v_mfma_f32_16x16x32_bf16 v[72:75], v[178:181], v[202:205], v[72:75]
	v_mfma_f32_16x16x32_bf16 v[68:71], v[170:173], v[210:213], v[68:71]
	v_mfma_f32_16x16x32_bf16 v[64:67], v[178:181], v[210:213], v[64:67]
	v_mfma_f32_16x16x32_bf16 v[112:115], v[174:177], v[190:193], v[112:115]
	v_mfma_f32_16x16x32_bf16 v[104:107], v[182:185], v[190:193], v[104:107]
	v_mfma_f32_16x16x32_bf16 v[96:99], v[174:177], v[198:201], v[96:99]
	v_mfma_f32_16x16x32_bf16 v[88:91], v[182:185], v[198:201], v[88:91]
	v_mfma_f32_16x16x32_bf16 v[80:83], v[174:177], v[206:209], v[80:83]
	v_mfma_f32_16x16x32_bf16 v[72:75], v[182:185], v[206:209], v[72:75]
	v_mfma_f32_16x16x32_bf16 v[68:71], v[174:177], v[214:217], v[68:71]
	v_mfma_f32_16x16x32_bf16 v[64:67], v[182:185], v[214:217], v[64:67]
	s_setprio 0
	s_barrier
	s_add_i32 s52, s52, s3
	s_mov_b32 m0, s52
	ds_read_b128 v[186:189], v153 offset:49152
	ds_read_b128 v[190:193], v153 offset:50176
	ds_read_b128 v[194:197], v153 offset:51200
	ds_read_b128 v[198:201], v153 offset:52224
	ds_read_b128 v[202:205], v153 offset:53248
	ds_read_b128 v[206:209], v153 offset:54272
	ds_read_b128 v[210:213], v153 offset:55296
	ds_read_b128 v[214:217], v153 offset:56320
	s_add_u32 s98, s68, 0x80
	s_addc_u32 s99, s69, 0
	global_load_lds_dwordx4 v132, s[98:99]
	s_add_i32 m0, s52, 0x2000
	s_add_u32 s68, s68, 0x80080
	s_addc_u32 s69, s69, 0
	s_add_i32 s52, s53, s3
	global_load_lds_dwordx4 v128, s[98:99]
	s_mov_b32 m0, s52
	s_nop 0
	global_load_lds_dwordx4 v132, s[68:69]
	s_add_i32 m0, s52, 0x2000
	s_nop 0
	global_load_lds_dwordx4 v128, s[68:69]
	s_mov_b32 m0, s77
	s_nop 0
	s_add_u32 s100, s70, 0xfff80080
	s_addc_u32 s101, s71, -1
	global_load_lds_dwordx4 v134, s[100:101]
	s_mov_b32 m0, s78
	s_nop 0
	global_load_lds_dwordx4 v130, s[100:101]
	s_waitcnt vmcnt(8)
	s_waitcnt lgkmcnt(0)
	s_barrier
	s_setprio 1
	s_waitcnt lgkmcnt(0)
	v_mfma_f32_16x16x32_bf16 v[60:63], v[154:157], v[186:189], v[60:63]
	v_mfma_f32_16x16x32_bf16 v[56:59], v[162:165], v[186:189], v[56:59]
	v_mfma_f32_16x16x32_bf16 v[52:55], v[154:157], v[194:197], v[52:55]
	v_mfma_f32_16x16x32_bf16 v[44:47], v[162:165], v[194:197], v[44:47]
	v_mfma_f32_16x16x32_bf16 v[36:39], v[154:157], v[202:205], v[36:39]
	v_mfma_f32_16x16x32_bf16 v[28:31], v[162:165], v[202:205], v[28:31]
	v_mfma_f32_16x16x32_bf16 v[20:23], v[154:157], v[210:213], v[20:23]
	v_mfma_f32_16x16x32_bf16 v[12:15], v[162:165], v[210:213], v[12:15]
	v_mfma_f32_16x16x32_bf16 v[60:63], v[158:161], v[190:193], v[60:63]
	v_mfma_f32_16x16x32_bf16 v[56:59], v[166:169], v[190:193], v[56:59]
	v_mfma_f32_16x16x32_bf16 v[52:55], v[158:161], v[198:201], v[52:55]
	v_mfma_f32_16x16x32_bf16 v[44:47], v[166:169], v[198:201], v[44:47]
	v_mfma_f32_16x16x32_bf16 v[36:39], v[158:161], v[206:209], v[36:39]
	v_mfma_f32_16x16x32_bf16 v[28:31], v[166:169], v[206:209], v[28:31]
	v_mfma_f32_16x16x32_bf16 v[20:23], v[158:161], v[214:217], v[20:23]
	v_mfma_f32_16x16x32_bf16 v[12:15], v[166:169], v[214:217], v[12:15]
	s_setprio 0
	s_setprio 1
	v_mfma_f32_16x16x32_bf16 v[48:51], v[170:173], v[186:189], v[48:51]
	v_mfma_f32_16x16x32_bf16 v[40:43], v[178:181], v[186:189], v[40:43]
	v_mfma_f32_16x16x32_bf16 v[32:35], v[170:173], v[194:197], v[32:35]
	v_mfma_f32_16x16x32_bf16 v[24:27], v[178:181], v[194:197], v[24:27]
	v_mfma_f32_16x16x32_bf16 v[16:19], v[170:173], v[202:205], v[16:19]
	v_mfma_f32_16x16x32_bf16 v[8:11], v[178:181], v[202:205], v[8:11]
	v_mfma_f32_16x16x32_bf16 v[4:7], v[170:173], v[210:213], v[4:7]
	v_mfma_f32_16x16x32_bf16 v[0:3], v[178:181], v[210:213], v[0:3]
	v_mfma_f32_16x16x32_bf16 v[48:51], v[174:177], v[190:193], v[48:51]
	v_mfma_f32_16x16x32_bf16 v[40:43], v[182:185], v[190:193], v[40:43]
	v_mfma_f32_16x16x32_bf16 v[32:35], v[174:177], v[198:201], v[32:35]
	v_mfma_f32_16x16x32_bf16 v[24:27], v[182:185], v[198:201], v[24:27]
	v_mfma_f32_16x16x32_bf16 v[16:19], v[174:177], v[206:209], v[16:19]
	v_mfma_f32_16x16x32_bf16 v[8:11], v[182:185], v[206:209], v[8:11]
	v_mfma_f32_16x16x32_bf16 v[4:7], v[174:177], v[214:217], v[4:7]
	v_mfma_f32_16x16x32_bf16 v[0:3], v[182:185], v[214:217], v[0:3]
	s_setprio 0
	s_barrier
	s_add_i32 s91, s91, 2
	s_add_u32 s54, s54, 0x100
	s_addc_u32 s55, s55, 0
	s_add_u32 s89, s89, 0x100
	s_addc_u32 s90, s90, 0
	s_cmp_gt_u32 s91, 29
	s_cbranch_scc0 .LBB0_61
	s_and_b64 vcc, exec, s[10:11]
	s_cbranch_vccz .LBB0_64
	s_barrier
; __device__ __forceinline__ unsigned cvt_pk_bf16(float lo, float hi) { unsigned r; asm volatile("v_cvt_pk_bf16_f32 %0, %1, %2" : "=v"(r) : "v"(lo), "v"(hi)); return r; }
;     __device__ __forceinline__ void operator()(const f32x4 (&acc)[2][2][4][2], const Unit& u, int wr, int wc, int fr, int fq) const {
;         const int row0 = u.pm * BM + wr * 64 + fr; int colt = u.pn * BM; const int sec = colt >> 10; colt &= 1023;
;         bf16_t* base = O + (size_t)sec * SEC; const int col0 = colt + wc * 32 + 8 * fq;
; #pragma unroll
;         for (int ai = 0; ai < 2; ++ai)
; #pragma unroll
;             for (int m = 0; m < 4; ++m) { bf16_t* rowp = base + (size_t)(row0 + ai * HALF + m * 16) * 1024 + col0;
; #pragma unroll
;                 for (int bj = 0; bj < 2; ++bj) { const f32x4 v0 = acc[ai][bj][m][0], v1 = acc[ai][bj][m][1];
;                     u32x4 w; w.x = cvt_pk_bf16(v0[0], v0[1]); w.y = cvt_pk_bf16(v0[2], v0[3]); w.z = cvt_pk_bf16(v1[0], v1[1]); w.w = cvt_pk_bf16(v1[2], v1[3]);
;                     *(u32x4*)(rowp + bj * HALF) = w; } }
.LBB0_64:
	s_ashr_i32 s54, s86, 2
	s_lshl_b32 s21, s86, 9
	s_ashr_i32 s55, s54, 31
	s_and_b32 s21, s21, 0x600
	s_lshl_b64 s[54:55], s[54:55], 26
	s_lshl_b32 s96, s46, 19
	s_add_u32 s54, s38, s54
	s_addc_u32 s55, s39, s55
	s_add_u32 s96, s96, s21
	s_add_u32 s96, s54, s96
	s_addc_u32 s97, s55, 0
	v_cvt_pk_bf16_f32 v124, v124, v125
	v_cvt_pk_bf16_f32 v125, v126, v127
	v_cvt_pk_bf16_f32 v126, v120, v121
	v_cvt_pk_bf16_f32 v127, v122, v123
	global_store_dwordx4 v230, v[124:127], s[96:97] sc0 sc1
	v_cvt_pk_bf16_f32 v112, v112, v113
	v_cvt_pk_bf16_f32 v113, v114, v115
	v_cvt_pk_bf16_f32 v114, v104, v105
	v_cvt_pk_bf16_f32 v115, v106, v107
	global_store_dwordx4 v230, v[112:115], s[96:97] offset:256 sc0 sc1
	v_cvt_pk_bf16_f32 v104, v116, v117
	v_cvt_pk_bf16_f32 v105, v118, v119
	v_cvt_pk_bf16_f32 v106, v108, v109
	v_cvt_pk_bf16_f32 v107, v110, v111
	s_add_u32 s98, s96, 0x8000
	s_addc_u32 s99, s97, 0
	global_store_dwordx4 v230, v[104:107], s[98:99] sc0 sc1
	v_cvt_pk_bf16_f32 v96, v96, v97
	v_cvt_pk_bf16_f32 v97, v98, v99
	v_cvt_pk_bf16_f32 v98, v88, v89
	v_cvt_pk_bf16_f32 v99, v90, v91
	global_store_dwordx4 v230, v[96:99], s[98:99] offset:256 sc0 sc1
	v_cvt_pk_bf16_f32 v88, v100, v101
	v_cvt_pk_bf16_f32 v89, v102, v103
	v_cvt_pk_bf16_f32 v90, v92, v93
	v_cvt_pk_bf16_f32 v91, v94, v95
	s_add_u32 s98, s96, 0x10000
	s_addc_u32 s99, s97, 0
	global_store_dwordx4 v230, v[88:91], s[98:99] sc0 sc1
	v_cvt_pk_bf16_f32 v80, v80, v81
	v_cvt_pk_bf16_f32 v81, v82, v83
	v_cvt_pk_bf16_f32 v82, v72, v73
	v_cvt_pk_bf16_f32 v83, v74, v75
	global_store_dwordx4 v230, v[80:83], s[98:99] offset:256 sc0 sc1
	v_cvt_pk_bf16_f32 v72, v84, v85
	v_cvt_pk_bf16_f32 v73, v86, v87
	v_cvt_pk_bf16_f32 v74, v76, v77
	v_cvt_pk_bf16_f32 v75, v78, v79
	s_add_u32 s98, s96, 0x18000
	s_addc_u32 s99, s97, 0
	global_store_dwordx4 v230, v[72:75], s[98:99] sc0 sc1
	v_cvt_pk_bf16_f32 v68, v68, v69
	v_cvt_pk_bf16_f32 v69, v70, v71
	v_cvt_pk_bf16_f32 v70, v64, v65
	v_cvt_pk_bf16_f32 v71, v66, v67
	global_store_dwordx4 v230, v[68:71], s[98:99] offset:256 sc0 sc1
	v_cvt_pk_bf16_f32 v60, v60, v61
	v_cvt_pk_bf16_f32 v61, v62, v63
	v_cvt_pk_bf16_f32 v62, v56, v57
	v_cvt_pk_bf16_f32 v63, v58, v59
	s_add_u32 s98, s96, 0x40000
	s_addc_u32 s99, s97, 0
	global_store_dwordx4 v230, v[60:63], s[98:99] sc0 sc1
	v_cvt_pk_bf16_f32 v48, v48, v49
	v_cvt_pk_bf16_f32 v49, v50, v51
	v_cvt_pk_bf16_f32 v50, v40, v41
	v_cvt_pk_bf16_f32 v51, v42, v43
	global_store_dwordx4 v230, v[48:51], s[98:99] offset:256 sc0 sc1
	v_cvt_pk_bf16_f32 v40, v52, v53
	v_cvt_pk_bf16_f32 v41, v54, v55
	v_cvt_pk_bf16_f32 v42, v44, v45
	v_cvt_pk_bf16_f32 v43, v46, v47
	s_add_u32 s98, s96, 0x48000
	s_addc_u32 s99, s97, 0
	global_store_dwordx4 v230, v[40:43], s[98:99] sc0 sc1
	v_cvt_pk_bf16_f32 v32, v32, v33
	v_cvt_pk_bf16_f32 v33, v34, v35
	v_cvt_pk_bf16_f32 v34, v24, v25
	v_cvt_pk_bf16_f32 v35, v26, v27
	global_store_dwordx4 v230, v[32:35], s[98:99] offset:256 sc0 sc1
	v_cvt_pk_bf16_f32 v24, v36, v37
	v_cvt_pk_bf16_f32 v25, v38, v39
	v_cvt_pk_bf16_f32 v26, v28, v29
	v_cvt_pk_bf16_f32 v27, v30, v31
	s_add_u32 s98, s96, 0x50000
	s_addc_u32 s99, s97, 0
	global_store_dwordx4 v230, v[24:27], s[98:99] sc0 sc1
	v_cvt_pk_bf16_f32 v16, v16, v17
	v_cvt_pk_bf16_f32 v17, v18, v19
	v_cvt_pk_bf16_f32 v18, v8, v9
	v_cvt_pk_bf16_f32 v19, v10, v11
	global_store_dwordx4 v230, v[16:19], s[98:99] offset:256 sc0 sc1
	v_cvt_pk_bf16_f32 v8, v20, v21
	v_cvt_pk_bf16_f32 v9, v22, v23
	v_cvt_pk_bf16_f32 v10, v12, v13
	v_cvt_pk_bf16_f32 v11, v14, v15
	s_add_u32 s98, s96, 0x58000
	s_addc_u32 s99, s97, 0
	global_store_dwordx4 v230, v[8:11], s[98:99] sc0 sc1
	v_cvt_pk_bf16_f32 v4, v4, v5
	v_cvt_pk_bf16_f32 v5, v6, v7
	v_cvt_pk_bf16_f32 v6, v0, v1
	v_cvt_pk_bf16_f32 v7, v2, v3
	global_store_dwordx4 v230, v[4:7], s[98:99] offset:256 sc0 sc1
	s_andn2_b64 vcc, exec, s[0:1]
	s_mov_b64 s[0:1], -1
	s_cbranch_vccnz .LBB0_57
	s_andn2_b64 vcc, exec, s[6:7]
	s_cbranch_vccnz .LBB0_56
	s_barrier
	s_branch .LBB0_56

; #define PG8_STAGE(bufoff, gbase, voff) do { _Pragma("unroll") for (int _i = 0; _i < 2; ++_i) \
;         __builtin_amdgcn_global_load_lds((const unsigned*)((const char*)(gbase) + (voff)[_i]), (PG8_LAS unsigned*)(lds + (bufoff) + ldsw + _i * 8192), 16, 0, 0); } while (0)
; #define PG8_LDA(dst, b, h) do { _Pragma("unroll") for (int m = 0; m < 4; ++m) _Pragma("unroll") for (int k = 0; k < 2; ++k) dst[m][k] = *(const PG8_LAS bf16x8*)(lds + PG8_SA(b, h) + aoff + m * 2048 + k * 1024); } while (0)
; #define PG8_LDB(dst, b, h) do { _Pragma("unroll") for (int n = 0; n < 2; ++n) _Pragma("unroll") for (int k = 0; k < 2; ++k) dst[n][k] = *(const PG8_LAS bf16x8*)(lds + PG8_SB(b, h) + boff + n * 2048 + k * 1024); } while (0)
; #define PG8_MMA(ai, bj, At, Bt) do { __builtin_amdgcn_s_setprio(1); _Pragma("unroll") for (int m = 0; m < 4; ++m) _Pragma("unroll") for (int n = 0; n < 2; ++n) _Pragma("unroll") for (int k = 0; k < 2; ++k) \
;         acc[ai][bj][m][n] = __builtin_amdgcn_mfma_f32_16x16x32_bf16(Bt[n][k], At[m][k], acc[ai][bj][m][n], 0, 0, 0); __builtin_amdgcn_s_setprio(0); } while (0)
; #define PG8_WAIT_V(n) asm volatile("s_waitcnt vmcnt(" #n ")" ::: "memory")
; #define PG8_WAIT_L(n) asm volatile("s_waitcnt lgkmcnt(" #n ")" ::: "memory")
; #define PG8_BAR __builtin_amdgcn_s_barrier()
; #define PG8_SCHED __builtin_amdgcn_sched_barrier(0)
; template <class Epi, class Sched, bool ALIGN_EPI = false, bool SP2 = false>
; __device__ __forceinline__ void gemm_phase(PG8_LAS unsigned char* lds, const Gemm g, const Sched& S, const Epi& E) {
;     ...
;             if constexpr (SP2) {
;             PG8_LDB(B0, 0, 0); PG8_LDB(B1, 0, 1); PG8_SCHED; PG8_LDA(At, 0, 0); PG8_STAGE(PG8_SA(1, 1), a1 + hstep, voffA);
;             PG8_WAIT_V(8); PG8_WAIT_L(0); PG8_BAR; PG8_MMA(0, 0, At, B0); PG8_MMA(0, 1, At, B1); PG8_BAR; PG8_SCHED;
;             PG8_LDA(At, 0, 1); PG8_STAGE(PG8_SB(0, 0), b2, voffB); PG8_STAGE(PG8_SB(0, 1), b2 + hstep, voffB); PG8_STAGE(PG8_SA(0, 0), a2, voffA);
;             PG8_WAIT_V(8); PG8_WAIT_L(0); PG8_BAR; PG8_MMA(1, 0, At, B0); PG8_MMA(1, 1, At, B1); PG8_BAR; PG8_SCHED;
.LBB0_664:
	ds_read_b128 v[144:147], v153
	ds_read_b128 v[158:161], v153 offset:1024
	ds_read_b128 v[162:165], v153 offset:2048
	ds_read_b128 v[166:169], v153 offset:3072
	ds_read_b128 v[170:173], v154
	ds_read_b128 v[174:177], v154 offset:1024
	ds_read_b128 v[178:181], v154 offset:2048
	ds_read_b128 v[182:185], v154 offset:3072
	s_add_u32 s44, s42, 0xfff80080
	s_addc_u32 s45, s43, -1
	s_cmp_eq_u32 s63, 28
	s_cselect_b32 s47, s21, s45
	s_cselect_b32 s46, s31, s44
	s_cselect_b32 s45, s19, s62
	s_cselect_b32 s44, s60, s61
	s_add_i32 m0, s41, 0xc000
	ds_read_b128 v[186:189], v155
	ds_read_b128 v[190:193], v155 offset:1024
	ds_read_b128 v[194:197], v155 offset:2048
	ds_read_b128 v[198:201], v155 offset:3072
	ds_read_b128 v[202:205], v155 offset:4096
	ds_read_b128 v[206:209], v155 offset:5120
	ds_read_b128 v[210:213], v155 offset:6144
	ds_read_b128 v[214:217], v155 offset:7168
	global_load_lds_dwordx4 v136, s[42:43]
	s_add_i32 m0, s41, 0xe000
	s_nop 0
	global_load_lds_dwordx4 v138, s[42:43]
	s_waitcnt vmcnt(8)
	s_waitcnt lgkmcnt(0)
	s_barrier
	s_setprio 1
	s_waitcnt lgkmcnt(0)
	v_mfma_f32_16x16x32_bf16 v[124:127], v[144:147], v[186:189], v[124:127]
	v_mfma_f32_16x16x32_bf16 v[120:123], v[162:165], v[186:189], v[120:123]
	v_mfma_f32_16x16x32_bf16 v[108:111], v[144:147], v[194:197], v[108:111]
	v_mfma_f32_16x16x32_bf16 v[104:107], v[162:165], v[194:197], v[104:107]
	v_mfma_f32_16x16x32_bf16 v[92:95], v[144:147], v[202:205], v[92:95]
	v_mfma_f32_16x16x32_bf16 v[88:91], v[162:165], v[202:205], v[88:91]
	v_mfma_f32_16x16x32_bf16 v[76:79], v[144:147], v[210:213], v[76:79]
	v_mfma_f32_16x16x32_bf16 v[72:75], v[162:165], v[210:213], v[72:75]
	v_mfma_f32_16x16x32_bf16 v[124:127], v[158:161], v[190:193], v[124:127]
	v_mfma_f32_16x16x32_bf16 v[120:123], v[166:169], v[190:193], v[120:123]
	v_mfma_f32_16x16x32_bf16 v[108:111], v[158:161], v[198:201], v[108:111]
	v_mfma_f32_16x16x32_bf16 v[104:107], v[166:169], v[198:201], v[104:107]
	v_mfma_f32_16x16x32_bf16 v[92:95], v[158:161], v[206:209], v[92:95]
	v_mfma_f32_16x16x32_bf16 v[88:91], v[166:169], v[206:209], v[88:91]
	v_mfma_f32_16x16x32_bf16 v[76:79], v[158:161], v[214:217], v[76:79]
	v_mfma_f32_16x16x32_bf16 v[72:75], v[166:169], v[214:217], v[72:75]
	s_setprio 0
	s_setprio 1
	v_mfma_f32_16x16x32_bf16 v[116:119], v[170:173], v[186:189], v[116:119]
	v_mfma_f32_16x16x32_bf16 v[112:115], v[178:181], v[186:189], v[112:115]
	v_mfma_f32_16x16x32_bf16 v[100:103], v[170:173], v[194:197], v[100:103]
	v_mfma_f32_16x16x32_bf16 v[96:99], v[178:181], v[194:197], v[96:99]
	v_mfma_f32_16x16x32_bf16 v[84:87], v[170:173], v[202:205], v[84:87]
	v_mfma_f32_16x16x32_bf16 v[80:83], v[178:181], v[202:205], v[80:83]
	v_mfma_f32_16x16x32_bf16 v[68:71], v[170:173], v[210:213], v[68:71]
	v_mfma_f32_16x16x32_bf16 v[64:67], v[178:181], v[210:213], v[64:67]
	v_mfma_f32_16x16x32_bf16 v[116:119], v[174:177], v[190:193], v[116:119]
	v_mfma_f32_16x16x32_bf16 v[112:115], v[182:185], v[190:193], v[112:115]
	v_mfma_f32_16x16x32_bf16 v[100:103], v[174:177], v[198:201], v[100:103]
	v_mfma_f32_16x16x32_bf16 v[96:99], v[182:185], v[198:201], v[96:99]
	v_mfma_f32_16x16x32_bf16 v[84:87], v[174:177], v[206:209], v[84:87]
	v_mfma_f32_16x16x32_bf16 v[80:83], v[182:185], v[206:209], v[80:83]
	v_mfma_f32_16x16x32_bf16 v[68:71], v[174:177], v[214:217], v[68:71]
	v_mfma_f32_16x16x32_bf16 v[64:67], v[182:185], v[214:217], v[64:67]
	s_setprio 0
	s_barrier
	s_add_i32 s64, s58, s49
	s_mov_b32 m0, s64
	ds_read_b128 v[186:189], v155 offset:16384
	ds_read_b128 v[190:193], v155 offset:17408
	ds_read_b128 v[194:197], v155 offset:18432
	ds_read_b128 v[198:201], v155 offset:19456
	ds_read_b128 v[202:205], v155 offset:20480
	ds_read_b128 v[206:209], v155 offset:21504
	ds_read_b128 v[210:213], v155 offset:22528
	ds_read_b128 v[214:217], v155 offset:23552
	global_load_lds_dwordx4 v130, s[44:45]
	s_add_i32 m0, s64, 0x2000
	s_add_u32 s64, s44, 0x80000
	s_addc_u32 s65, s45, 0
	s_add_i32 s66, s59, s49
	global_load_lds_dwordx4 v134, s[44:45]
	s_mov_b32 m0, s66
	s_nop 0
	global_load_lds_dwordx4 v130, s[64:65]
	s_add_i32 m0, s66, 0x2000
	s_nop 0
	global_load_lds_dwordx4 v134, s[64:65]
	s_mov_b32 m0, s41
	s_nop 0
	global_load_lds_dwordx4 v128, s[46:47]
	s_mov_b32 m0, s50
	s_nop 0
	global_load_lds_dwordx4 v132, s[46:47]
	s_waitcnt vmcnt(8)
	s_waitcnt lgkmcnt(0)
	s_barrier
	s_setprio 1
	s_waitcnt lgkmcnt(0)
	v_mfma_f32_16x16x32_bf16 v[60:63], v[144:147], v[186:189], v[60:63]
	v_mfma_f32_16x16x32_bf16 v[56:59], v[162:165], v[186:189], v[56:59]
	v_mfma_f32_16x16x32_bf16 v[44:47], v[144:147], v[194:197], v[44:47]
	v_mfma_f32_16x16x32_bf16 v[40:43], v[162:165], v[194:197], v[40:43]
	v_mfma_f32_16x16x32_bf16 v[28:31], v[144:147], v[202:205], v[28:31]
	v_mfma_f32_16x16x32_bf16 v[24:27], v[162:165], v[202:205], v[24:27]
	v_mfma_f32_16x16x32_bf16 v[12:15], v[144:147], v[210:213], v[12:15]
	v_mfma_f32_16x16x32_bf16 v[8:11], v[162:165], v[210:213], v[8:11]
	v_mfma_f32_16x16x32_bf16 v[60:63], v[158:161], v[190:193], v[60:63]
	v_mfma_f32_16x16x32_bf16 v[56:59], v[166:169], v[190:193], v[56:59]
	v_mfma_f32_16x16x32_bf16 v[44:47], v[158:161], v[198:201], v[44:47]
	v_mfma_f32_16x16x32_bf16 v[40:43], v[166:169], v[198:201], v[40:43]
	v_mfma_f32_16x16x32_bf16 v[28:31], v[158:161], v[206:209], v[28:31]
	v_mfma_f32_16x16x32_bf16 v[24:27], v[166:169], v[206:209], v[24:27]
	v_mfma_f32_16x16x32_bf16 v[12:15], v[158:161], v[214:217], v[12:15]
	v_mfma_f32_16x16x32_bf16 v[8:11], v[166:169], v[214:217], v[8:11]
	s_setprio 0
	s_setprio 1
	v_mfma_f32_16x16x32_bf16 v[52:55], v[170:173], v[186:189], v[52:55]
	v_mfma_f32_16x16x32_bf16 v[48:51], v[178:181], v[186:189], v[48:51]
	v_mfma_f32_16x16x32_bf16 v[36:39], v[170:173], v[194:197], v[36:39]
	v_mfma_f32_16x16x32_bf16 v[32:35], v[178:181], v[194:197], v[32:35]
	v_mfma_f32_16x16x32_bf16 v[20:23], v[170:173], v[202:205], v[20:23]
	v_mfma_f32_16x16x32_bf16 v[16:19], v[178:181], v[202:205], v[16:19]
	v_mfma_f32_16x16x32_bf16 v[4:7], v[170:173], v[210:213], v[4:7]
	v_mfma_f32_16x16x32_bf16 v[0:3], v[178:181], v[210:213], v[0:3]
	v_mfma_f32_16x16x32_bf16 v[52:55], v[174:177], v[190:193], v[52:55]
	v_mfma_f32_16x16x32_bf16 v[48:51], v[182:185], v[190:193], v[48:51]
	v_mfma_f32_16x16x32_bf16 v[36:39], v[174:177], v[198:201], v[36:39]
	v_mfma_f32_16x16x32_bf16 v[32:35], v[182:185], v[198:201], v[32:35]
	v_mfma_f32_16x16x32_bf16 v[20:23], v[174:177], v[206:209], v[20:23]
	v_mfma_f32_16x16x32_bf16 v[16:19], v[182:185], v[206:209], v[16:19]
	v_mfma_f32_16x16x32_bf16 v[4:7], v[174:177], v[214:217], v[4:7]
	v_mfma_f32_16x16x32_bf16 v[0:3], v[182:185], v[214:217], v[0:3]
	s_setprio 0
	s_barrier
; #define PG8_STAGE(bufoff, gbase, voff) do { _Pragma("unroll") for (int _i = 0; _i < 2; ++_i) \
;         __builtin_amdgcn_global_load_lds((const unsigned*)((const char*)(gbase) + (voff)[_i]), (PG8_LAS unsigned*)(lds + (bufoff) + ldsw + _i * 8192), 16, 0, 0); } while (0)
; #define PG8_LDA(dst, b, h) do { _Pragma("unroll") for (int m = 0; m < 4; ++m) _Pragma("unroll") for (int k = 0; k < 2; ++k) dst[m][k] = *(const PG8_LAS bf16x8*)(lds + PG8_SA(b, h) + aoff + m * 2048 + k * 1024); } while (0)
; #define PG8_LDB(dst, b, h) do { _Pragma("unroll") for (int n = 0; n < 2; ++n) _Pragma("unroll") for (int k = 0; k < 2; ++k) dst[n][k] = *(const PG8_LAS bf16x8*)(lds + PG8_SB(b, h) + boff + n * 2048 + k * 1024); } while (0)
; #define PG8_MMA(ai, bj, At, Bt) do { __builtin_amdgcn_s_setprio(1); _Pragma("unroll") for (int m = 0; m < 4; ++m) _Pragma("unroll") for (int n = 0; n < 2; ++n) _Pragma("unroll") for (int k = 0; k < 2; ++k) \
;         acc[ai][bj][m][n] = __builtin_amdgcn_mfma_f32_16x16x32_bf16(Bt[n][k], At[m][k], acc[ai][bj][m][n], 0, 0, 0); __builtin_amdgcn_s_setprio(0); } while (0)
; #define PG8_WAIT_V(n) asm volatile("s_waitcnt vmcnt(" #n ")" ::: "memory")
; #define PG8_WAIT_L(n) asm volatile("s_waitcnt lgkmcnt(" #n ")" ::: "memory")
; #define PG8_BAR __builtin_amdgcn_s_barrier()
; #define PG8_SCHED __builtin_amdgcn_sched_barrier(0)
; template <class Epi, class Sched, bool ALIGN_EPI = false, bool SP2 = false>
; __device__ __forceinline__ void gemm_phase(PG8_LAS unsigned char* lds, const Gemm g, const Sched& S, const Epi& E) {
;     ...
;             PG8_LDB(B0, 1, 0); PG8_LDB(B1, 1, 1); PG8_SCHED; PG8_LDA(At, 1, 0); PG8_STAGE(PG8_SA(0, 1), a2 + hstep, voffA);
;             PG8_WAIT_V(8); PG8_WAIT_L(0); PG8_BAR; PG8_MMA(0, 0, At, B0); PG8_MMA(0, 1, At, B1); PG8_BAR; PG8_SCHED;
;             PG8_LDA(At, 1, 1); PG8_STAGE(PG8_SB(1, 0), b3, voffB); PG8_STAGE(PG8_SB(1, 1), b3 + hstep, voffB); PG8_STAGE(PG8_SA(1, 0), a3, voffA);
;             PG8_WAIT_V(8); PG8_WAIT_L(0); PG8_BAR; PG8_MMA(1, 0, At, B0); PG8_MMA(1, 1, At, B1); PG8_BAR; PG8_SCHED;
	s_add_i32 s64, 0, 0x18000
	v_add_u32_e32 v157, s64, v151
	s_add_i32 s65, 0, 0x1c000
	ds_read_b128 v[144:147], v157
	ds_read_b128 v[158:161], v157 offset:1024
	ds_read_b128 v[162:165], v157 offset:2048
	ds_read_b128 v[166:169], v157 offset:3072
	v_add_u32_e32 v157, s65, v151
	ds_read_b128 v[170:173], v157
	ds_read_b128 v[174:177], v157 offset:1024
	ds_read_b128 v[178:181], v157 offset:2048
	ds_read_b128 v[182:185], v157 offset:3072
	s_add_u32 s46, s46, 0x80000
	s_addc_u32 s47, s47, 0
	s_mov_b32 m0, s51
	ds_read_b128 v[186:189], v155 offset:32768
	ds_read_b128 v[190:193], v155 offset:33792
	ds_read_b128 v[194:197], v155 offset:34816
	ds_read_b128 v[198:201], v155 offset:35840
	ds_read_b128 v[202:205], v155 offset:36864
	ds_read_b128 v[206:209], v155 offset:37888
	ds_read_b128 v[210:213], v155 offset:38912
	ds_read_b128 v[214:217], v155 offset:39936
	global_load_lds_dwordx4 v128, s[46:47]
	s_mov_b32 m0, s52
	s_nop 0
	global_load_lds_dwordx4 v132, s[46:47]
	s_waitcnt vmcnt(8)
	s_waitcnt lgkmcnt(0)
	s_barrier
	s_setprio 1
	s_waitcnt lgkmcnt(0)
	v_mfma_f32_16x16x32_bf16 v[124:127], v[144:147], v[186:189], v[124:127]
	v_mfma_f32_16x16x32_bf16 v[120:123], v[162:165], v[186:189], v[120:123]
	v_mfma_f32_16x16x32_bf16 v[108:111], v[144:147], v[194:197], v[108:111]
	v_mfma_f32_16x16x32_bf16 v[104:107], v[162:165], v[194:197], v[104:107]
	v_mfma_f32_16x16x32_bf16 v[92:95], v[144:147], v[202:205], v[92:95]
	v_mfma_f32_16x16x32_bf16 v[88:91], v[162:165], v[202:205], v[88:91]
	v_mfma_f32_16x16x32_bf16 v[76:79], v[144:147], v[210:213], v[76:79]
	v_mfma_f32_16x16x32_bf16 v[72:75], v[162:165], v[210:213], v[72:75]
	v_mfma_f32_16x16x32_bf16 v[124:127], v[158:161], v[190:193], v[124:127]
	v_mfma_f32_16x16x32_bf16 v[120:123], v[166:169], v[190:193], v[120:123]
	v_mfma_f32_16x16x32_bf16 v[108:111], v[158:161], v[198:201], v[108:111]
	v_mfma_f32_16x16x32_bf16 v[104:107], v[166:169], v[198:201], v[104:107]
	v_mfma_f32_16x16x32_bf16 v[92:95], v[158:161], v[206:209], v[92:95]
	v_mfma_f32_16x16x32_bf16 v[88:91], v[166:169], v[206:209], v[88:91]
	v_mfma_f32_16x16x32_bf16 v[76:79], v[158:161], v[214:217], v[76:79]
	v_mfma_f32_16x16x32_bf16 v[72:75], v[166:169], v[214:217], v[72:75]
	s_setprio 0
	s_setprio 1
	v_mfma_f32_16x16x32_bf16 v[116:119], v[170:173], v[186:189], v[116:119]
	v_mfma_f32_16x16x32_bf16 v[112:115], v[178:181], v[186:189], v[112:115]
	v_mfma_f32_16x16x32_bf16 v[100:103], v[170:173], v[194:197], v[100:103]
	v_mfma_f32_16x16x32_bf16 v[96:99], v[178:181], v[194:197], v[96:99]
	v_mfma_f32_16x16x32_bf16 v[84:87], v[170:173], v[202:205], v[84:87]
	v_mfma_f32_16x16x32_bf16 v[80:83], v[178:181], v[202:205], v[80:83]
	v_mfma_f32_16x16x32_bf16 v[68:71], v[170:173], v[210:213], v[68:71]
	v_mfma_f32_16x16x32_bf16 v[64:67], v[178:181], v[210:213], v[64:67]
	v_mfma_f32_16x16x32_bf16 v[116:119], v[174:177], v[190:193], v[116:119]
	v_mfma_f32_16x16x32_bf16 v[112:115], v[182:185], v[190:193], v[112:115]
	v_mfma_f32_16x16x32_bf16 v[100:103], v[174:177], v[198:201], v[100:103]
	v_mfma_f32_16x16x32_bf16 v[96:99], v[182:185], v[198:201], v[96:99]
	v_mfma_f32_16x16x32_bf16 v[84:87], v[174:177], v[206:209], v[84:87]
	v_mfma_f32_16x16x32_bf16 v[80:83], v[182:185], v[206:209], v[80:83]
	v_mfma_f32_16x16x32_bf16 v[68:71], v[174:177], v[214:217], v[68:71]
	v_mfma_f32_16x16x32_bf16 v[64:67], v[182:185], v[214:217], v[64:67]
	s_setprio 0
	s_barrier
	s_mov_b64 s[68:69], s[46:47]
	s_add_i32 s46, s64, s49
	s_mov_b32 m0, s46
	ds_read_b128 v[186:189], v155 offset:49152
	ds_read_b128 v[190:193], v155 offset:50176
	ds_read_b128 v[194:197], v155 offset:51200
	ds_read_b128 v[198:201], v155 offset:52224
	ds_read_b128 v[202:205], v155 offset:53248
	ds_read_b128 v[206:209], v155 offset:54272
	ds_read_b128 v[210:213], v155 offset:55296
	ds_read_b128 v[214:217], v155 offset:56320
	s_add_u32 s70, s44, 0x80
	s_addc_u32 s71, s45, 0
	global_load_lds_dwordx4 v130, s[70:71]
	s_add_i32 m0, s46, 0x2000
	s_add_u32 s44, s44, 0x80080
	s_addc_u32 s45, s45, 0
	s_add_i32 s46, s65, s49
	global_load_lds_dwordx4 v134, s[70:71]
	s_mov_b32 m0, s46
	s_nop 0
	global_load_lds_dwordx4 v130, s[44:45]
	s_add_i32 m0, s46, 0x2000
	s_nop 0
	global_load_lds_dwordx4 v134, s[44:45]
	s_mov_b32 m0, s54
	s_nop 0
	s_add_u32 s72, s68, 0xfff80080
	s_addc_u32 s73, s69, -1
	global_load_lds_dwordx4 v128, s[72:73]
	s_mov_b32 m0, s55
	s_nop 0
	global_load_lds_dwordx4 v132, s[72:73]
	s_waitcnt vmcnt(8)
	s_waitcnt lgkmcnt(0)
	s_barrier
	s_setprio 1
	s_waitcnt lgkmcnt(0)
	v_mfma_f32_16x16x32_bf16 v[60:63], v[144:147], v[186:189], v[60:63]
	v_mfma_f32_16x16x32_bf16 v[56:59], v[162:165], v[186:189], v[56:59]
	v_mfma_f32_16x16x32_bf16 v[44:47], v[144:147], v[194:197], v[44:47]
	v_mfma_f32_16x16x32_bf16 v[40:43], v[162:165], v[194:197], v[40:43]
	v_mfma_f32_16x16x32_bf16 v[28:31], v[144:147], v[202:205], v[28:31]
	v_mfma_f32_16x16x32_bf16 v[24:27], v[162:165], v[202:205], v[24:27]
	v_mfma_f32_16x16x32_bf16 v[12:15], v[144:147], v[210:213], v[12:15]
	v_mfma_f32_16x16x32_bf16 v[8:11], v[162:165], v[210:213], v[8:11]
	v_mfma_f32_16x16x32_bf16 v[60:63], v[158:161], v[190:193], v[60:63]
	v_mfma_f32_16x16x32_bf16 v[56:59], v[166:169], v[190:193], v[56:59]
	v_mfma_f32_16x16x32_bf16 v[44:47], v[158:161], v[198:201], v[44:47]
	v_mfma_f32_16x16x32_bf16 v[40:43], v[166:169], v[198:201], v[40:43]
	v_mfma_f32_16x16x32_bf16 v[28:31], v[158:161], v[206:209], v[28:31]
	v_mfma_f32_16x16x32_bf16 v[24:27], v[166:169], v[206:209], v[24:27]
	v_mfma_f32_16x16x32_bf16 v[12:15], v[158:161], v[214:217], v[12:15]
	v_mfma_f32_16x16x32_bf16 v[8:11], v[166:169], v[214:217], v[8:11]
	s_setprio 0
	s_setprio 1
	v_mfma_f32_16x16x32_bf16 v[52:55], v[170:173], v[186:189], v[52:55]
	v_mfma_f32_16x16x32_bf16 v[48:51], v[178:181], v[186:189], v[48:51]
	v_mfma_f32_16x16x32_bf16 v[36:39], v[170:173], v[194:197], v[36:39]
	v_mfma_f32_16x16x32_bf16 v[32:35], v[178:181], v[194:197], v[32:35]
	v_mfma_f32_16x16x32_bf16 v[20:23], v[170:173], v[202:205], v[20:23]
	v_mfma_f32_16x16x32_bf16 v[16:19], v[178:181], v[202:205], v[16:19]
	v_mfma_f32_16x16x32_bf16 v[4:7], v[170:173], v[210:213], v[4:7]
	v_mfma_f32_16x16x32_bf16 v[0:3], v[178:181], v[210:213], v[0:3]
	v_mfma_f32_16x16x32_bf16 v[52:55], v[174:177], v[190:193], v[52:55]
	v_mfma_f32_16x16x32_bf16 v[48:51], v[182:185], v[190:193], v[48:51]
	v_mfma_f32_16x16x32_bf16 v[36:39], v[174:177], v[198:201], v[36:39]
	v_mfma_f32_16x16x32_bf16 v[32:35], v[182:185], v[198:201], v[32:35]
	v_mfma_f32_16x16x32_bf16 v[20:23], v[174:177], v[206:209], v[20:23]
	v_mfma_f32_16x16x32_bf16 v[16:19], v[182:185], v[206:209], v[16:19]
	v_mfma_f32_16x16x32_bf16 v[4:7], v[174:177], v[214:217], v[4:7]
	v_mfma_f32_16x16x32_bf16 v[0:3], v[182:185], v[214:217], v[0:3]
	s_setprio 0
	s_barrier
	s_add_i32 s63, s63, 2
	s_add_u32 s42, s42, 0x100
	s_addc_u32 s43, s43, 0
	s_add_u32 s61, s61, 0x100
	s_addc_u32 s62, s62, 0
	s_cmp_gt_u32 s63, 29
	s_cbranch_scc0 .LBB0_664
	s_and_b64 vcc, exec, s[16:17]
	s_cbranch_vccz .LBB0_667
	s_barrier

; #define PG8_STAGE(bufoff, gbase, voff) do { _Pragma("unroll") for (int _i = 0; _i < 2; ++_i) \
;         __builtin_amdgcn_global_load_lds((const unsigned*)((const char*)(gbase) + (voff)[_i]), (PG8_LAS unsigned*)(lds + (bufoff) + ldsw + _i * 8192), 16, 0, 0); } while (0)
; #define PG8_LDA(dst, b, h) do { _Pragma("unroll") for (int m = 0; m < 4; ++m) _Pragma("unroll") for (int k = 0; k < 2; ++k) dst[m][k] = *(const PG8_LAS bf16x8*)(lds + PG8_SA(b, h) + aoff + m * 2048 + k * 1024); } while (0)
; #define PG8_LDB(dst, b, h) do { _Pragma("unroll") for (int n = 0; n < 2; ++n) _Pragma("unroll") for (int k = 0; k < 2; ++k) dst[n][k] = *(const PG8_LAS bf16x8*)(lds + PG8_SB(b, h) + boff + n * 2048 + k * 1024); } while (0)
; #define PG8_MMA(ai, bj, At, Bt) do { __builtin_amdgcn_s_setprio(1); _Pragma("unroll") for (int m = 0; m < 4; ++m) _Pragma("unroll") for (int n = 0; n < 2; ++n) _Pragma("unroll") for (int k = 0; k < 2; ++k) \
;         acc[ai][bj][m][n] = __builtin_amdgcn_mfma_f32_16x16x32_bf16(Bt[n][k], At[m][k], acc[ai][bj][m][n], 0, 0, 0); __builtin_amdgcn_s_setprio(0); } while (0)
; #define PG8_WAIT_V(n) asm volatile("s_waitcnt vmcnt(" #n ")" ::: "memory")
; #define PG8_WAIT_L(n) asm volatile("s_waitcnt lgkmcnt(" #n ")" ::: "memory")
; #define PG8_BAR __builtin_amdgcn_s_barrier()
; #define PG8_SCHED __builtin_amdgcn_sched_barrier(0)
; template <class Epi, class Sched, bool ALIGN_EPI = false, bool SP2 = false>
; __device__ __forceinline__ void gemm_phase(PG8_LAS unsigned char* lds, const Gemm g, const Sched& S, const Epi& E) {
;     ...
;             if constexpr (SP2) {
;             PG8_LDB(B0, 0, 0); PG8_LDB(B1, 0, 1); PG8_SCHED; PG8_LDA(At, 0, 0); PG8_STAGE(PG8_SA(1, 1), a1 + hstep, voffA);
;             PG8_WAIT_V(8); PG8_WAIT_L(0); PG8_BAR; PG8_MMA(0, 0, At, B0); PG8_MMA(0, 1, At, B1); PG8_BAR; PG8_SCHED;
;             PG8_LDA(At, 0, 1); PG8_STAGE(PG8_SB(0, 0), b2, voffB); PG8_STAGE(PG8_SB(0, 1), b2 + hstep, voffB); PG8_STAGE(PG8_SA(0, 0), a2, voffA);
;             PG8_WAIT_V(8); PG8_WAIT_L(0); PG8_BAR; PG8_MMA(1, 0, At, B0); PG8_MMA(1, 1, At, B1); PG8_BAR; PG8_SCHED;
.LBB0_705:
	ds_read_b128 v[144:147], v151
	ds_read_b128 v[156:159], v151 offset:1024
	ds_read_b128 v[160:163], v151 offset:2048
	ds_read_b128 v[164:167], v151 offset:3072
	ds_read_b128 v[168:171], v152
	ds_read_b128 v[172:175], v152 offset:1024
	ds_read_b128 v[176:179], v152 offset:2048
	ds_read_b128 v[180:183], v152 offset:3072
	s_add_u32 s36, s30, 0xfff80080
	s_addc_u32 s37, s31, -1
	s_cmp_eq_u32 s62, 28
	s_cselect_b32 s39, s21, s37
	s_cselect_b32 s38, s58, s36
	s_cselect_b32 s37, s19, s61
	s_cselect_b32 s36, s59, s60
	s_add_i32 m0, s46, 0xc000
	ds_read_b128 v[184:187], v153
	ds_read_b128 v[188:191], v153 offset:1024
	ds_read_b128 v[192:195], v153 offset:2048
	ds_read_b128 v[196:199], v153 offset:3072
	ds_read_b128 v[200:203], v153 offset:4096
	ds_read_b128 v[204:207], v153 offset:5120
	ds_read_b128 v[208:211], v153 offset:6144
	ds_read_b128 v[212:215], v153 offset:7168
	global_load_lds_dwordx4 v136, s[30:31]
	s_add_i32 m0, s46, 0xe000
	s_nop 0
	global_load_lds_dwordx4 v138, s[30:31]
	s_waitcnt vmcnt(8)
	s_waitcnt lgkmcnt(0)
	s_barrier
	s_setprio 1
	s_waitcnt lgkmcnt(0)
	v_mfma_f32_16x16x32_bf16 v[116:119], v[144:147], v[184:187], v[116:119]
	v_mfma_f32_16x16x32_bf16 v[112:115], v[160:163], v[184:187], v[112:115]
	v_mfma_f32_16x16x32_bf16 v[100:103], v[144:147], v[192:195], v[100:103]
	v_mfma_f32_16x16x32_bf16 v[96:99], v[160:163], v[192:195], v[96:99]
	v_mfma_f32_16x16x32_bf16 v[84:87], v[144:147], v[200:203], v[84:87]
	v_mfma_f32_16x16x32_bf16 v[80:83], v[160:163], v[200:203], v[80:83]
	v_mfma_f32_16x16x32_bf16 v[72:75], v[144:147], v[208:211], v[72:75]
	v_mfma_f32_16x16x32_bf16 v[64:67], v[160:163], v[208:211], v[64:67]
	v_mfma_f32_16x16x32_bf16 v[116:119], v[156:159], v[188:191], v[116:119]
	v_mfma_f32_16x16x32_bf16 v[112:115], v[164:167], v[188:191], v[112:115]
	v_mfma_f32_16x16x32_bf16 v[100:103], v[156:159], v[196:199], v[100:103]
	v_mfma_f32_16x16x32_bf16 v[96:99], v[164:167], v[196:199], v[96:99]
	v_mfma_f32_16x16x32_bf16 v[84:87], v[156:159], v[204:207], v[84:87]
	v_mfma_f32_16x16x32_bf16 v[80:83], v[164:167], v[204:207], v[80:83]
	v_mfma_f32_16x16x32_bf16 v[72:75], v[156:159], v[212:215], v[72:75]
	v_mfma_f32_16x16x32_bf16 v[64:67], v[164:167], v[212:215], v[64:67]
	s_setprio 0
	s_setprio 1
	v_mfma_f32_16x16x32_bf16 v[124:127], v[168:171], v[184:187], v[124:127]
	v_mfma_f32_16x16x32_bf16 v[120:123], v[176:179], v[184:187], v[120:123]
	v_mfma_f32_16x16x32_bf16 v[108:111], v[168:171], v[192:195], v[108:111]
	v_mfma_f32_16x16x32_bf16 v[104:107], v[176:179], v[192:195], v[104:107]
	v_mfma_f32_16x16x32_bf16 v[92:95], v[168:171], v[200:203], v[92:95]
	v_mfma_f32_16x16x32_bf16 v[88:91], v[176:179], v[200:203], v[88:91]
	v_mfma_f32_16x16x32_bf16 v[76:79], v[168:171], v[208:211], v[76:79]
	v_mfma_f32_16x16x32_bf16 v[68:71], v[176:179], v[208:211], v[68:71]
	v_mfma_f32_16x16x32_bf16 v[124:127], v[172:175], v[188:191], v[124:127]
	v_mfma_f32_16x16x32_bf16 v[120:123], v[180:183], v[188:191], v[120:123]
	v_mfma_f32_16x16x32_bf16 v[108:111], v[172:175], v[196:199], v[108:111]
	v_mfma_f32_16x16x32_bf16 v[104:107], v[180:183], v[196:199], v[104:107]
	v_mfma_f32_16x16x32_bf16 v[92:95], v[172:175], v[204:207], v[92:95]
	v_mfma_f32_16x16x32_bf16 v[88:91], v[180:183], v[204:207], v[88:91]
	v_mfma_f32_16x16x32_bf16 v[76:79], v[172:175], v[212:215], v[76:79]
	v_mfma_f32_16x16x32_bf16 v[68:71], v[180:183], v[212:215], v[68:71]
	s_setprio 0
	s_barrier
	s_add_i32 s63, s54, s43
	s_mov_b32 m0, s63
	ds_read_b128 v[184:187], v153 offset:16384
	ds_read_b128 v[188:191], v153 offset:17408
	ds_read_b128 v[192:195], v153 offset:18432
	ds_read_b128 v[196:199], v153 offset:19456
	ds_read_b128 v[200:203], v153 offset:20480
	ds_read_b128 v[204:207], v153 offset:21504
	ds_read_b128 v[208:211], v153 offset:22528
	ds_read_b128 v[212:215], v153 offset:23552
	global_load_lds_dwordx4 v132, s[36:37]
	s_add_i32 m0, s63, 0x2000
	s_add_u32 s64, s36, 0x80000
	s_addc_u32 s65, s37, 0
	s_add_i32 s63, s55, s43
	global_load_lds_dwordx4 v128, s[36:37]
	s_mov_b32 m0, s63
	s_nop 0
	global_load_lds_dwordx4 v132, s[64:65]
	s_add_i32 m0, s63, 0x2000
	s_nop 0
	global_load_lds_dwordx4 v128, s[64:65]
	s_mov_b32 m0, s46
	s_nop 0
	global_load_lds_dwordx4 v134, s[38:39]
	s_mov_b32 m0, s47
	s_nop 0
	global_load_lds_dwordx4 v130, s[38:39]
	s_waitcnt vmcnt(8)
	s_waitcnt lgkmcnt(0)
	s_barrier
	s_setprio 1
	s_waitcnt lgkmcnt(0)
	v_mfma_f32_16x16x32_bf16 v[56:59], v[144:147], v[184:187], v[56:59]
	v_mfma_f32_16x16x32_bf16 v[48:51], v[160:163], v[184:187], v[48:51]
	v_mfma_f32_16x16x32_bf16 v[40:43], v[144:147], v[192:195], v[40:43]
	v_mfma_f32_16x16x32_bf16 v[32:35], v[160:163], v[192:195], v[32:35]
	v_mfma_f32_16x16x32_bf16 v[24:27], v[144:147], v[200:203], v[24:27]
	v_mfma_f32_16x16x32_bf16 v[16:19], v[160:163], v[200:203], v[16:19]
	v_mfma_f32_16x16x32_bf16 v[8:11], v[144:147], v[208:211], v[8:11]
	v_mfma_f32_16x16x32_bf16 v[0:3], v[160:163], v[208:211], v[0:3]
	v_mfma_f32_16x16x32_bf16 v[56:59], v[156:159], v[188:191], v[56:59]
	v_mfma_f32_16x16x32_bf16 v[48:51], v[164:167], v[188:191], v[48:51]
	v_mfma_f32_16x16x32_bf16 v[40:43], v[156:159], v[196:199], v[40:43]
	v_mfma_f32_16x16x32_bf16 v[32:35], v[164:167], v[196:199], v[32:35]
	v_mfma_f32_16x16x32_bf16 v[24:27], v[156:159], v[204:207], v[24:27]
	v_mfma_f32_16x16x32_bf16 v[16:19], v[164:167], v[204:207], v[16:19]
	v_mfma_f32_16x16x32_bf16 v[8:11], v[156:159], v[212:215], v[8:11]
	v_mfma_f32_16x16x32_bf16 v[0:3], v[164:167], v[212:215], v[0:3]
	s_setprio 0
	s_setprio 1
	v_mfma_f32_16x16x32_bf16 v[60:63], v[168:171], v[184:187], v[60:63]
	v_mfma_f32_16x16x32_bf16 v[52:55], v[176:179], v[184:187], v[52:55]
	v_mfma_f32_16x16x32_bf16 v[44:47], v[168:171], v[192:195], v[44:47]
	v_mfma_f32_16x16x32_bf16 v[36:39], v[176:179], v[192:195], v[36:39]
	v_mfma_f32_16x16x32_bf16 v[28:31], v[168:171], v[200:203], v[28:31]
	v_mfma_f32_16x16x32_bf16 v[20:23], v[176:179], v[200:203], v[20:23]
	v_mfma_f32_16x16x32_bf16 v[12:15], v[168:171], v[208:211], v[12:15]
	v_mfma_f32_16x16x32_bf16 v[4:7], v[176:179], v[208:211], v[4:7]
	v_mfma_f32_16x16x32_bf16 v[60:63], v[172:175], v[188:191], v[60:63]
	v_mfma_f32_16x16x32_bf16 v[52:55], v[180:183], v[188:191], v[52:55]
	v_mfma_f32_16x16x32_bf16 v[44:47], v[172:175], v[196:199], v[44:47]
	v_mfma_f32_16x16x32_bf16 v[36:39], v[180:183], v[196:199], v[36:39]
	v_mfma_f32_16x16x32_bf16 v[28:31], v[172:175], v[204:207], v[28:31]
	v_mfma_f32_16x16x32_bf16 v[20:23], v[180:183], v[204:207], v[20:23]
	v_mfma_f32_16x16x32_bf16 v[12:15], v[172:175], v[212:215], v[12:15]
	v_mfma_f32_16x16x32_bf16 v[4:7], v[180:183], v[212:215], v[4:7]
	s_setprio 0
	s_barrier
; #define PG8_STAGE(bufoff, gbase, voff) do { _Pragma("unroll") for (int _i = 0; _i < 2; ++_i) \
;         __builtin_amdgcn_global_load_lds((const unsigned*)((const char*)(gbase) + (voff)[_i]), (PG8_LAS unsigned*)(lds + (bufoff) + ldsw + _i * 8192), 16, 0, 0); } while (0)
; #define PG8_LDA(dst, b, h) do { _Pragma("unroll") for (int m = 0; m < 4; ++m) _Pragma("unroll") for (int k = 0; k < 2; ++k) dst[m][k] = *(const PG8_LAS bf16x8*)(lds + PG8_SA(b, h) + aoff + m * 2048 + k * 1024); } while (0)
; #define PG8_LDB(dst, b, h) do { _Pragma("unroll") for (int n = 0; n < 2; ++n) _Pragma("unroll") for (int k = 0; k < 2; ++k) dst[n][k] = *(const PG8_LAS bf16x8*)(lds + PG8_SB(b, h) + boff + n * 2048 + k * 1024); } while (0)
; #define PG8_MMA(ai, bj, At, Bt) do { __builtin_amdgcn_s_setprio(1); _Pragma("unroll") for (int m = 0; m < 4; ++m) _Pragma("unroll") for (int n = 0; n < 2; ++n) _Pragma("unroll") for (int k = 0; k < 2; ++k) \
;         acc[ai][bj][m][n] = __builtin_amdgcn_mfma_f32_16x16x32_bf16(Bt[n][k], At[m][k], acc[ai][bj][m][n], 0, 0, 0); __builtin_amdgcn_s_setprio(0); } while (0)
; #define PG8_WAIT_V(n) asm volatile("s_waitcnt vmcnt(" #n ")" ::: "memory")
; #define PG8_WAIT_L(n) asm volatile("s_waitcnt lgkmcnt(" #n ")" ::: "memory")
; #define PG8_BAR __builtin_amdgcn_s_barrier()
; #define PG8_SCHED __builtin_amdgcn_sched_barrier(0)
; template <class Epi, class Sched, bool ALIGN_EPI = false, bool SP2 = false>
; __device__ __forceinline__ void gemm_phase(PG8_LAS unsigned char* lds, const Gemm g, const Sched& S, const Epi& E) {
;     ...
;             PG8_LDB(B0, 1, 0); PG8_LDB(B1, 1, 1); PG8_SCHED; PG8_LDA(At, 1, 0); PG8_STAGE(PG8_SA(0, 1), a2 + hstep, voffA);
;             PG8_WAIT_V(8); PG8_WAIT_L(0); PG8_BAR; PG8_MMA(0, 0, At, B0); PG8_MMA(0, 1, At, B1); PG8_BAR; PG8_SCHED;
;             PG8_LDA(At, 1, 1); PG8_STAGE(PG8_SB(1, 0), b3, voffB); PG8_STAGE(PG8_SB(1, 1), b3 + hstep, voffB); PG8_STAGE(PG8_SA(1, 0), a3, voffA);
;             PG8_WAIT_V(8); PG8_WAIT_L(0); PG8_BAR; PG8_MMA(1, 0, At, B0); PG8_MMA(1, 1, At, B1); PG8_BAR; PG8_SCHED;
	s_add_i32 s63, 0, 0x18000
	v_add_u32_e32 v155, s63, v149
	s_add_i32 s64, 0, 0x1c000
	ds_read_b128 v[144:147], v155
	ds_read_b128 v[156:159], v155 offset:1024
	ds_read_b128 v[160:163], v155 offset:2048
	ds_read_b128 v[164:167], v155 offset:3072
	v_add_u32_e32 v155, s64, v149
	ds_read_b128 v[168:171], v155
	ds_read_b128 v[172:175], v155 offset:1024
	ds_read_b128 v[176:179], v155 offset:2048
	ds_read_b128 v[180:183], v155 offset:3072
	s_add_u32 s38, s38, 0x80000
	s_addc_u32 s39, s39, 0
	s_mov_b32 m0, s48
	ds_read_b128 v[184:187], v153 offset:32768
	ds_read_b128 v[188:191], v153 offset:33792
	ds_read_b128 v[192:195], v153 offset:34816
	ds_read_b128 v[196:199], v153 offset:35840
	ds_read_b128 v[200:203], v153 offset:36864
	ds_read_b128 v[204:207], v153 offset:37888
	ds_read_b128 v[208:211], v153 offset:38912
	ds_read_b128 v[212:215], v153 offset:39936
	global_load_lds_dwordx4 v134, s[38:39]
	s_mov_b32 m0, s49
	s_nop 0
	global_load_lds_dwordx4 v130, s[38:39]
	s_waitcnt vmcnt(8)
	s_waitcnt lgkmcnt(0)
	s_barrier
	s_setprio 1
	s_waitcnt lgkmcnt(0)
	v_mfma_f32_16x16x32_bf16 v[116:119], v[144:147], v[184:187], v[116:119]
	v_mfma_f32_16x16x32_bf16 v[112:115], v[160:163], v[184:187], v[112:115]
	v_mfma_f32_16x16x32_bf16 v[100:103], v[144:147], v[192:195], v[100:103]
	v_mfma_f32_16x16x32_bf16 v[96:99], v[160:163], v[192:195], v[96:99]
	v_mfma_f32_16x16x32_bf16 v[84:87], v[144:147], v[200:203], v[84:87]
	v_mfma_f32_16x16x32_bf16 v[80:83], v[160:163], v[200:203], v[80:83]
	v_mfma_f32_16x16x32_bf16 v[72:75], v[144:147], v[208:211], v[72:75]
	v_mfma_f32_16x16x32_bf16 v[64:67], v[160:163], v[208:211], v[64:67]
	v_mfma_f32_16x16x32_bf16 v[116:119], v[156:159], v[188:191], v[116:119]
	v_mfma_f32_16x16x32_bf16 v[112:115], v[164:167], v[188:191], v[112:115]
	v_mfma_f32_16x16x32_bf16 v[100:103], v[156:159], v[196:199], v[100:103]
	v_mfma_f32_16x16x32_bf16 v[96:99], v[164:167], v[196:199], v[96:99]
	v_mfma_f32_16x16x32_bf16 v[84:87], v[156:159], v[204:207], v[84:87]
	v_mfma_f32_16x16x32_bf16 v[80:83], v[164:167], v[204:207], v[80:83]
	v_mfma_f32_16x16x32_bf16 v[72:75], v[156:159], v[212:215], v[72:75]
	v_mfma_f32_16x16x32_bf16 v[64:67], v[164:167], v[212:215], v[64:67]
	s_setprio 0
	s_setprio 1
	v_mfma_f32_16x16x32_bf16 v[124:127], v[168:171], v[184:187], v[124:127]
	v_mfma_f32_16x16x32_bf16 v[120:123], v[176:179], v[184:187], v[120:123]
	v_mfma_f32_16x16x32_bf16 v[108:111], v[168:171], v[192:195], v[108:111]
	v_mfma_f32_16x16x32_bf16 v[104:107], v[176:179], v[192:195], v[104:107]
	v_mfma_f32_16x16x32_bf16 v[92:95], v[168:171], v[200:203], v[92:95]
	v_mfma_f32_16x16x32_bf16 v[88:91], v[176:179], v[200:203], v[88:91]
	v_mfma_f32_16x16x32_bf16 v[76:79], v[168:171], v[208:211], v[76:79]
	v_mfma_f32_16x16x32_bf16 v[68:71], v[176:179], v[208:211], v[68:71]
	v_mfma_f32_16x16x32_bf16 v[124:127], v[172:175], v[188:191], v[124:127]
	v_mfma_f32_16x16x32_bf16 v[120:123], v[180:183], v[188:191], v[120:123]
	v_mfma_f32_16x16x32_bf16 v[108:111], v[172:175], v[196:199], v[108:111]
	v_mfma_f32_16x16x32_bf16 v[104:107], v[180:183], v[196:199], v[104:107]
	v_mfma_f32_16x16x32_bf16 v[92:95], v[172:175], v[204:207], v[92:95]
	v_mfma_f32_16x16x32_bf16 v[88:91], v[180:183], v[204:207], v[88:91]
	v_mfma_f32_16x16x32_bf16 v[76:79], v[172:175], v[212:215], v[76:79]
	v_mfma_f32_16x16x32_bf16 v[68:71], v[180:183], v[212:215], v[68:71]
	s_setprio 0
	s_barrier
	s_mov_b64 s[66:67], s[38:39]
	s_add_i32 s38, s63, s43
	s_mov_b32 m0, s38
	ds_read_b128 v[184:187], v153 offset:49152
	ds_read_b128 v[188:191], v153 offset:50176
	ds_read_b128 v[192:195], v153 offset:51200
	ds_read_b128 v[196:199], v153 offset:52224
	ds_read_b128 v[200:203], v153 offset:53248
	ds_read_b128 v[204:207], v153 offset:54272
	ds_read_b128 v[208:211], v153 offset:55296
	ds_read_b128 v[212:215], v153 offset:56320
	s_add_u32 s68, s36, 0x80
	s_addc_u32 s69, s37, 0
	global_load_lds_dwordx4 v132, s[68:69]
	s_add_i32 m0, s38, 0x2000
	s_add_u32 s36, s36, 0x80080
	s_addc_u32 s37, s37, 0
	s_add_i32 s38, s64, s43
	global_load_lds_dwordx4 v128, s[68:69]
	s_mov_b32 m0, s38
	s_nop 0
	global_load_lds_dwordx4 v132, s[36:37]
	s_add_i32 m0, s38, 0x2000
	s_nop 0
	global_load_lds_dwordx4 v128, s[36:37]
	s_mov_b32 m0, s51
	s_nop 0
	s_add_u32 s70, s66, 0xfff80080
	s_addc_u32 s71, s67, -1
	global_load_lds_dwordx4 v134, s[70:71]
	s_mov_b32 m0, s52
	s_nop 0
	global_load_lds_dwordx4 v130, s[70:71]
	s_waitcnt vmcnt(8)
	s_waitcnt lgkmcnt(0)
	s_barrier
	s_setprio 1
	s_waitcnt lgkmcnt(0)
	v_mfma_f32_16x16x32_bf16 v[56:59], v[144:147], v[184:187], v[56:59]
	v_mfma_f32_16x16x32_bf16 v[48:51], v[160:163], v[184:187], v[48:51]
	v_mfma_f32_16x16x32_bf16 v[40:43], v[144:147], v[192:195], v[40:43]
	v_mfma_f32_16x16x32_bf16 v[32:35], v[160:163], v[192:195], v[32:35]
	v_mfma_f32_16x16x32_bf16 v[24:27], v[144:147], v[200:203], v[24:27]
	v_mfma_f32_16x16x32_bf16 v[16:19], v[160:163], v[200:203], v[16:19]
	v_mfma_f32_16x16x32_bf16 v[8:11], v[144:147], v[208:211], v[8:11]
	v_mfma_f32_16x16x32_bf16 v[0:3], v[160:163], v[208:211], v[0:3]
	v_mfma_f32_16x16x32_bf16 v[56:59], v[156:159], v[188:191], v[56:59]
	v_mfma_f32_16x16x32_bf16 v[48:51], v[164:167], v[188:191], v[48:51]
	v_mfma_f32_16x16x32_bf16 v[40:43], v[156:159], v[196:199], v[40:43]
	v_mfma_f32_16x16x32_bf16 v[32:35], v[164:167], v[196:199], v[32:35]
	v_mfma_f32_16x16x32_bf16 v[24:27], v[156:159], v[204:207], v[24:27]
	v_mfma_f32_16x16x32_bf16 v[16:19], v[164:167], v[204:207], v[16:19]
	v_mfma_f32_16x16x32_bf16 v[8:11], v[156:159], v[212:215], v[8:11]
	v_mfma_f32_16x16x32_bf16 v[0:3], v[164:167], v[212:215], v[0:3]
	s_setprio 0
	s_setprio 1
	v_mfma_f32_16x16x32_bf16 v[60:63], v[168:171], v[184:187], v[60:63]
	v_mfma_f32_16x16x32_bf16 v[52:55], v[176:179], v[184:187], v[52:55]
	v_mfma_f32_16x16x32_bf16 v[44:47], v[168:171], v[192:195], v[44:47]
	v_mfma_f32_16x16x32_bf16 v[36:39], v[176:179], v[192:195], v[36:39]
	v_mfma_f32_16x16x32_bf16 v[28:31], v[168:171], v[200:203], v[28:31]
	v_mfma_f32_16x16x32_bf16 v[20:23], v[176:179], v[200:203], v[20:23]
	v_mfma_f32_16x16x32_bf16 v[12:15], v[168:171], v[208:211], v[12:15]
	v_mfma_f32_16x16x32_bf16 v[4:7], v[176:179], v[208:211], v[4:7]
	v_mfma_f32_16x16x32_bf16 v[60:63], v[172:175], v[188:191], v[60:63]
	v_mfma_f32_16x16x32_bf16 v[52:55], v[180:183], v[188:191], v[52:55]
	v_mfma_f32_16x16x32_bf16 v[44:47], v[172:175], v[196:199], v[44:47]
	v_mfma_f32_16x16x32_bf16 v[36:39], v[180:183], v[196:199], v[36:39]
	v_mfma_f32_16x16x32_bf16 v[28:31], v[172:175], v[204:207], v[28:31]
	v_mfma_f32_16x16x32_bf16 v[20:23], v[180:183], v[204:207], v[20:23]
	v_mfma_f32_16x16x32_bf16 v[12:15], v[172:175], v[212:215], v[12:15]
	v_mfma_f32_16x16x32_bf16 v[4:7], v[180:183], v[212:215], v[4:7]
	s_setprio 0
	s_barrier
	s_add_i32 s62, s62, 2
	s_add_u32 s30, s30, 0x100
	s_addc_u32 s31, s31, 0
	s_add_u32 s60, s60, 0x100
	s_addc_u32 s61, s61, 0
	s_cmp_gt_u32 s62, 29
	s_cbranch_scc0 .LBB0_705
	s_and_b64 vcc, exec, s[16:17]
	s_cbranch_vccz .LBB0_708
	s_barrier

; #define PG8_STAGE(bufoff, gbase, voff) do { _Pragma("unroll") for (int _i = 0; _i < 2; ++_i) \
;         __builtin_amdgcn_global_load_lds((const unsigned*)((const char*)(gbase) + (voff)[_i]), (PG8_LAS unsigned*)(lds + (bufoff) + ldsw + _i * 8192), 16, 0, 0); } while (0)
; #define PG8_LDA(dst, b, h) do { _Pragma("unroll") for (int m = 0; m < 4; ++m) _Pragma("unroll") for (int k = 0; k < 2; ++k) dst[m][k] = *(const PG8_LAS bf16x8*)(lds + PG8_SA(b, h) + aoff + m * 2048 + k * 1024); } while (0)
; #define PG8_LDB(dst, b, h) do { _Pragma("unroll") for (int n = 0; n < 2; ++n) _Pragma("unroll") for (int k = 0; k < 2; ++k) dst[n][k] = *(const PG8_LAS bf16x8*)(lds + PG8_SB(b, h) + boff + n * 2048 + k * 1024); } while (0)
; #define PG8_MMA(ai, bj, At, Bt) do { __builtin_amdgcn_s_setprio(1); _Pragma("unroll") for (int m = 0; m < 4; ++m) _Pragma("unroll") for (int n = 0; n < 2; ++n) _Pragma("unroll") for (int k = 0; k < 2; ++k) \
;         acc[ai][bj][m][n] = __builtin_amdgcn_mfma_f32_16x16x32_bf16(Bt[n][k], At[m][k], acc[ai][bj][m][n], 0, 0, 0); __builtin_amdgcn_s_setprio(0); } while (0)
; #define PG8_WAIT_V(n) asm volatile("s_waitcnt vmcnt(" #n ")" ::: "memory")
; #define PG8_WAIT_L(n) asm volatile("s_waitcnt lgkmcnt(" #n ")" ::: "memory")
; #define PG8_BAR __builtin_amdgcn_s_barrier()
; #define PG8_SCHED __builtin_amdgcn_sched_barrier(0)
; template <class Epi, class Sched, bool ALIGN_EPI = false, bool SP2 = false>
; __device__ __forceinline__ void gemm_phase(PG8_LAS unsigned char* lds, const Gemm g, const Sched& S, const Epi& E) {
;     ...
;             if constexpr (SP2) {
;             PG8_LDB(B0, 0, 0); PG8_LDB(B1, 0, 1); PG8_SCHED; PG8_LDA(At, 0, 0); PG8_STAGE(PG8_SA(1, 1), a1 + hstep, voffA);
;             PG8_WAIT_V(8); PG8_WAIT_L(0); PG8_BAR; PG8_MMA(0, 0, At, B0); PG8_MMA(0, 1, At, B1); PG8_BAR; PG8_SCHED;
;             PG8_LDA(At, 0, 1); PG8_STAGE(PG8_SB(0, 0), b2, voffB); PG8_STAGE(PG8_SB(0, 1), b2 + hstep, voffB); PG8_STAGE(PG8_SA(0, 0), a2, voffA);
;             PG8_WAIT_V(8); PG8_WAIT_L(0); PG8_BAR; PG8_MMA(1, 0, At, B0); PG8_MMA(1, 1, At, B1); PG8_BAR; PG8_SCHED;
.LBB0_742:
	ds_read_b128 v[144:147], v153
	ds_read_b128 v[156:159], v153 offset:1024
	ds_read_b128 v[160:163], v153 offset:2048
	ds_read_b128 v[164:167], v153 offset:3072
	ds_read_b128 v[168:171], v154
	ds_read_b128 v[172:175], v154 offset:1024
	ds_read_b128 v[176:179], v154 offset:2048
	ds_read_b128 v[180:183], v154 offset:3072
	s_add_u32 s24, s22, 0xffea0080
	s_addc_u32 s25, s23, -1
	s_cmpk_eq_i32 s57, 0x54
	s_cselect_b32 s29, s5, s25
	s_cselect_b32 s28, s4, s24
	s_cselect_b32 s25, s21, s56
	s_cselect_b32 s24, s20, s55
	s_add_i32 m0, s37, 0xc000
	ds_read_b128 v[184:187], v155
	ds_read_b128 v[188:191], v155 offset:1024
	ds_read_b128 v[192:195], v155 offset:2048
	ds_read_b128 v[196:199], v155 offset:3072
	ds_read_b128 v[200:203], v155 offset:4096
	ds_read_b128 v[204:207], v155 offset:5120
	ds_read_b128 v[208:211], v155 offset:6144
	ds_read_b128 v[212:215], v155 offset:7168
	global_load_lds_dwordx4 v136, s[22:23]
	s_add_i32 m0, s37, 0xe000
	s_nop 0
	global_load_lds_dwordx4 v138, s[22:23]
	s_waitcnt vmcnt(8)
	s_waitcnt lgkmcnt(0)
	s_barrier
	s_setprio 1
	s_waitcnt lgkmcnt(0)
	v_mfma_f32_16x16x32_bf16 v[124:127], v[144:147], v[184:187], v[124:127]
	v_mfma_f32_16x16x32_bf16 v[120:123], v[160:163], v[184:187], v[120:123]
	v_mfma_f32_16x16x32_bf16 v[108:111], v[144:147], v[192:195], v[108:111]
	v_mfma_f32_16x16x32_bf16 v[104:107], v[160:163], v[192:195], v[104:107]
	v_mfma_f32_16x16x32_bf16 v[92:95], v[144:147], v[200:203], v[92:95]
	v_mfma_f32_16x16x32_bf16 v[88:91], v[160:163], v[200:203], v[88:91]
	v_mfma_f32_16x16x32_bf16 v[76:79], v[144:147], v[208:211], v[76:79]
	v_mfma_f32_16x16x32_bf16 v[72:75], v[160:163], v[208:211], v[72:75]
	v_mfma_f32_16x16x32_bf16 v[124:127], v[156:159], v[188:191], v[124:127]
	v_mfma_f32_16x16x32_bf16 v[120:123], v[164:167], v[188:191], v[120:123]
	v_mfma_f32_16x16x32_bf16 v[108:111], v[156:159], v[196:199], v[108:111]
	v_mfma_f32_16x16x32_bf16 v[104:107], v[164:167], v[196:199], v[104:107]
	v_mfma_f32_16x16x32_bf16 v[92:95], v[156:159], v[204:207], v[92:95]
	v_mfma_f32_16x16x32_bf16 v[88:91], v[164:167], v[204:207], v[88:91]
	v_mfma_f32_16x16x32_bf16 v[76:79], v[156:159], v[212:215], v[76:79]
	v_mfma_f32_16x16x32_bf16 v[72:75], v[164:167], v[212:215], v[72:75]
	s_setprio 0
	s_setprio 1
	v_mfma_f32_16x16x32_bf16 v[116:119], v[168:171], v[184:187], v[116:119]
	v_mfma_f32_16x16x32_bf16 v[112:115], v[176:179], v[184:187], v[112:115]
	v_mfma_f32_16x16x32_bf16 v[100:103], v[168:171], v[192:195], v[100:103]
	v_mfma_f32_16x16x32_bf16 v[96:99], v[176:179], v[192:195], v[96:99]
	v_mfma_f32_16x16x32_bf16 v[84:87], v[168:171], v[200:203], v[84:87]
	v_mfma_f32_16x16x32_bf16 v[80:83], v[176:179], v[200:203], v[80:83]
	v_mfma_f32_16x16x32_bf16 v[68:71], v[168:171], v[208:211], v[68:71]
	v_mfma_f32_16x16x32_bf16 v[64:67], v[176:179], v[208:211], v[64:67]
	v_mfma_f32_16x16x32_bf16 v[116:119], v[172:175], v[188:191], v[116:119]
	v_mfma_f32_16x16x32_bf16 v[112:115], v[180:183], v[188:191], v[112:115]
	v_mfma_f32_16x16x32_bf16 v[100:103], v[172:175], v[196:199], v[100:103]
	v_mfma_f32_16x16x32_bf16 v[96:99], v[180:183], v[196:199], v[96:99]
	v_mfma_f32_16x16x32_bf16 v[84:87], v[172:175], v[204:207], v[84:87]
	v_mfma_f32_16x16x32_bf16 v[80:83], v[180:183], v[204:207], v[80:83]
	v_mfma_f32_16x16x32_bf16 v[68:71], v[172:175], v[212:215], v[68:71]
	v_mfma_f32_16x16x32_bf16 v[64:67], v[180:183], v[212:215], v[64:67]
	s_setprio 0
	s_barrier
	s_add_i32 s58, s45, s36
	s_mov_b32 m0, s58
	ds_read_b128 v[184:187], v155 offset:16384
	ds_read_b128 v[188:191], v155 offset:17408
	ds_read_b128 v[192:195], v155 offset:18432
	ds_read_b128 v[196:199], v155 offset:19456
	ds_read_b128 v[200:203], v155 offset:20480
	ds_read_b128 v[204:207], v155 offset:21504
	ds_read_b128 v[208:211], v155 offset:22528
	ds_read_b128 v[212:215], v155 offset:23552
	global_load_lds_dwordx4 v130, s[24:25]
	s_add_i32 m0, s58, 0x2000
	s_add_u32 s58, s24, 0x160000
	s_addc_u32 s59, s25, 0
	s_add_i32 s60, s46, s36
	global_load_lds_dwordx4 v134, s[24:25]
	s_mov_b32 m0, s60
	s_nop 0
	global_load_lds_dwordx4 v130, s[58:59]
	s_add_i32 m0, s60, 0x2000
	s_nop 0
	global_load_lds_dwordx4 v134, s[58:59]
	s_mov_b32 m0, s37
	s_nop 0
	global_load_lds_dwordx4 v128, s[28:29]
	s_mov_b32 m0, s38
	s_nop 0
	global_load_lds_dwordx4 v132, s[28:29]
	s_waitcnt vmcnt(8)
	s_waitcnt lgkmcnt(0)
	s_barrier
	s_setprio 1
	s_waitcnt lgkmcnt(0)
	v_mfma_f32_16x16x32_bf16 v[60:63], v[144:147], v[184:187], v[60:63]
	v_mfma_f32_16x16x32_bf16 v[56:59], v[160:163], v[184:187], v[56:59]
	v_mfma_f32_16x16x32_bf16 v[44:47], v[144:147], v[192:195], v[44:47]
	v_mfma_f32_16x16x32_bf16 v[40:43], v[160:163], v[192:195], v[40:43]
	v_mfma_f32_16x16x32_bf16 v[28:31], v[144:147], v[200:203], v[28:31]
	v_mfma_f32_16x16x32_bf16 v[24:27], v[160:163], v[200:203], v[24:27]
	v_mfma_f32_16x16x32_bf16 v[12:15], v[144:147], v[208:211], v[12:15]
	v_mfma_f32_16x16x32_bf16 v[8:11], v[160:163], v[208:211], v[8:11]
	v_mfma_f32_16x16x32_bf16 v[60:63], v[156:159], v[188:191], v[60:63]
	v_mfma_f32_16x16x32_bf16 v[56:59], v[164:167], v[188:191], v[56:59]
	v_mfma_f32_16x16x32_bf16 v[44:47], v[156:159], v[196:199], v[44:47]
	v_mfma_f32_16x16x32_bf16 v[40:43], v[164:167], v[196:199], v[40:43]
	v_mfma_f32_16x16x32_bf16 v[28:31], v[156:159], v[204:207], v[28:31]
	v_mfma_f32_16x16x32_bf16 v[24:27], v[164:167], v[204:207], v[24:27]
	v_mfma_f32_16x16x32_bf16 v[12:15], v[156:159], v[212:215], v[12:15]
	v_mfma_f32_16x16x32_bf16 v[8:11], v[164:167], v[212:215], v[8:11]
	s_setprio 0
	s_setprio 1
	v_mfma_f32_16x16x32_bf16 v[52:55], v[168:171], v[184:187], v[52:55]
	v_mfma_f32_16x16x32_bf16 v[48:51], v[176:179], v[184:187], v[48:51]
	v_mfma_f32_16x16x32_bf16 v[36:39], v[168:171], v[192:195], v[36:39]
	v_mfma_f32_16x16x32_bf16 v[32:35], v[176:179], v[192:195], v[32:35]
	v_mfma_f32_16x16x32_bf16 v[20:23], v[168:171], v[200:203], v[20:23]
	v_mfma_f32_16x16x32_bf16 v[16:19], v[176:179], v[200:203], v[16:19]
	v_mfma_f32_16x16x32_bf16 v[4:7], v[168:171], v[208:211], v[4:7]
	v_mfma_f32_16x16x32_bf16 v[0:3], v[176:179], v[208:211], v[0:3]
	v_mfma_f32_16x16x32_bf16 v[52:55], v[172:175], v[188:191], v[52:55]
	v_mfma_f32_16x16x32_bf16 v[48:51], v[180:183], v[188:191], v[48:51]
	v_mfma_f32_16x16x32_bf16 v[36:39], v[172:175], v[196:199], v[36:39]
	v_mfma_f32_16x16x32_bf16 v[32:35], v[180:183], v[196:199], v[32:35]
	v_mfma_f32_16x16x32_bf16 v[20:23], v[172:175], v[204:207], v[20:23]
	v_mfma_f32_16x16x32_bf16 v[16:19], v[180:183], v[204:207], v[16:19]
	v_mfma_f32_16x16x32_bf16 v[4:7], v[172:175], v[212:215], v[4:7]
	v_mfma_f32_16x16x32_bf16 v[0:3], v[180:183], v[212:215], v[0:3]
	s_setprio 0
	s_barrier
; #define PG8_STAGE(bufoff, gbase, voff) do { _Pragma("unroll") for (int _i = 0; _i < 2; ++_i) \
;         __builtin_amdgcn_global_load_lds((const unsigned*)((const char*)(gbase) + (voff)[_i]), (PG8_LAS unsigned*)(lds + (bufoff) + ldsw + _i * 8192), 16, 0, 0); } while (0)
; #define PG8_LDA(dst, b, h) do { _Pragma("unroll") for (int m = 0; m < 4; ++m) _Pragma("unroll") for (int k = 0; k < 2; ++k) dst[m][k] = *(const PG8_LAS bf16x8*)(lds + PG8_SA(b, h) + aoff + m * 2048 + k * 1024); } while (0)
; #define PG8_LDB(dst, b, h) do { _Pragma("unroll") for (int n = 0; n < 2; ++n) _Pragma("unroll") for (int k = 0; k < 2; ++k) dst[n][k] = *(const PG8_LAS bf16x8*)(lds + PG8_SB(b, h) + boff + n * 2048 + k * 1024); } while (0)
; #define PG8_MMA(ai, bj, At, Bt) do { __builtin_amdgcn_s_setprio(1); _Pragma("unroll") for (int m = 0; m < 4; ++m) _Pragma("unroll") for (int n = 0; n < 2; ++n) _Pragma("unroll") for (int k = 0; k < 2; ++k) \
;         acc[ai][bj][m][n] = __builtin_amdgcn_mfma_f32_16x16x32_bf16(Bt[n][k], At[m][k], acc[ai][bj][m][n], 0, 0, 0); __builtin_amdgcn_s_setprio(0); } while (0)
; #define PG8_WAIT_V(n) asm volatile("s_waitcnt vmcnt(" #n ")" ::: "memory")
; #define PG8_WAIT_L(n) asm volatile("s_waitcnt lgkmcnt(" #n ")" ::: "memory")
; #define PG8_BAR __builtin_amdgcn_s_barrier()
; #define PG8_SCHED __builtin_amdgcn_sched_barrier(0)
; template <class Epi, class Sched, bool ALIGN_EPI = false, bool SP2 = false>
; __device__ __forceinline__ void gemm_phase(PG8_LAS unsigned char* lds, const Gemm g, const Sched& S, const Epi& E) {
;     ...
;             PG8_LDB(B0, 1, 0); PG8_LDB(B1, 1, 1); PG8_SCHED; PG8_LDA(At, 1, 0); PG8_STAGE(PG8_SA(0, 1), a2 + hstep, voffA);
;             PG8_WAIT_V(8); PG8_WAIT_L(0); PG8_BAR; PG8_MMA(0, 0, At, B0); PG8_MMA(0, 1, At, B1); PG8_BAR; PG8_SCHED;
;             PG8_LDA(At, 1, 1); PG8_STAGE(PG8_SB(1, 0), b3, voffB); PG8_STAGE(PG8_SB(1, 1), b3 + hstep, voffB); PG8_STAGE(PG8_SA(1, 0), a3, voffA);
;             PG8_WAIT_V(8); PG8_WAIT_L(0); PG8_BAR; PG8_MMA(1, 0, At, B0); PG8_MMA(1, 1, At, B1); PG8_BAR; PG8_SCHED;
	s_add_i32 s58, 0, 0x18000
	s_add_i32 s59, 0, 0x1c000
	v_add_u32_e32 v164, s58, v151
	v_add_u32_e32 v180, s59, v151
	ds_read_b128 v[144:147], v164
	ds_read_b128 v[156:159], v164 offset:1024
	ds_read_b128 v[160:163], v164 offset:2048
	ds_read_b128 v[164:167], v164 offset:3072
	ds_read_b128 v[168:171], v180
	ds_read_b128 v[172:175], v180 offset:1024
	ds_read_b128 v[176:179], v180 offset:2048
	ds_read_b128 v[180:183], v180 offset:3072
	s_add_u32 s28, s28, 0x160000
	s_addc_u32 s29, s29, 0
	s_mov_b32 m0, s39
	ds_read_b128 v[184:187], v155 offset:32768
	ds_read_b128 v[188:191], v155 offset:33792
	ds_read_b128 v[192:195], v155 offset:34816
	ds_read_b128 v[196:199], v155 offset:35840
	ds_read_b128 v[200:203], v155 offset:36864
	ds_read_b128 v[204:207], v155 offset:37888
	ds_read_b128 v[208:211], v155 offset:38912
	ds_read_b128 v[212:215], v155 offset:39936
	global_load_lds_dwordx4 v128, s[28:29]
	s_mov_b32 m0, s40
	s_nop 0
	global_load_lds_dwordx4 v132, s[28:29]
	s_waitcnt vmcnt(8)
	s_waitcnt lgkmcnt(0)
	s_barrier
	s_setprio 1
	s_waitcnt lgkmcnt(0)
	v_mfma_f32_16x16x32_bf16 v[124:127], v[144:147], v[184:187], v[124:127]
	v_mfma_f32_16x16x32_bf16 v[120:123], v[160:163], v[184:187], v[120:123]
	v_mfma_f32_16x16x32_bf16 v[108:111], v[144:147], v[192:195], v[108:111]
	v_mfma_f32_16x16x32_bf16 v[104:107], v[160:163], v[192:195], v[104:107]
	v_mfma_f32_16x16x32_bf16 v[92:95], v[144:147], v[200:203], v[92:95]
	v_mfma_f32_16x16x32_bf16 v[88:91], v[160:163], v[200:203], v[88:91]
	v_mfma_f32_16x16x32_bf16 v[76:79], v[144:147], v[208:211], v[76:79]
	v_mfma_f32_16x16x32_bf16 v[72:75], v[160:163], v[208:211], v[72:75]
	v_mfma_f32_16x16x32_bf16 v[124:127], v[156:159], v[188:191], v[124:127]
	v_mfma_f32_16x16x32_bf16 v[120:123], v[164:167], v[188:191], v[120:123]
	v_mfma_f32_16x16x32_bf16 v[108:111], v[156:159], v[196:199], v[108:111]
	v_mfma_f32_16x16x32_bf16 v[104:107], v[164:167], v[196:199], v[104:107]
	v_mfma_f32_16x16x32_bf16 v[92:95], v[156:159], v[204:207], v[92:95]
	v_mfma_f32_16x16x32_bf16 v[88:91], v[164:167], v[204:207], v[88:91]
	v_mfma_f32_16x16x32_bf16 v[76:79], v[156:159], v[212:215], v[76:79]
	v_mfma_f32_16x16x32_bf16 v[72:75], v[164:167], v[212:215], v[72:75]
	s_setprio 0
	s_setprio 1
	v_mfma_f32_16x16x32_bf16 v[116:119], v[168:171], v[184:187], v[116:119]
	v_mfma_f32_16x16x32_bf16 v[112:115], v[176:179], v[184:187], v[112:115]
	v_mfma_f32_16x16x32_bf16 v[100:103], v[168:171], v[192:195], v[100:103]
	v_mfma_f32_16x16x32_bf16 v[96:99], v[176:179], v[192:195], v[96:99]
	v_mfma_f32_16x16x32_bf16 v[84:87], v[168:171], v[200:203], v[84:87]
	v_mfma_f32_16x16x32_bf16 v[80:83], v[176:179], v[200:203], v[80:83]
	v_mfma_f32_16x16x32_bf16 v[68:71], v[168:171], v[208:211], v[68:71]
	v_mfma_f32_16x16x32_bf16 v[64:67], v[176:179], v[208:211], v[64:67]
	v_mfma_f32_16x16x32_bf16 v[116:119], v[172:175], v[188:191], v[116:119]
	v_mfma_f32_16x16x32_bf16 v[112:115], v[180:183], v[188:191], v[112:115]
	v_mfma_f32_16x16x32_bf16 v[100:103], v[172:175], v[196:199], v[100:103]
	v_mfma_f32_16x16x32_bf16 v[96:99], v[180:183], v[196:199], v[96:99]
	v_mfma_f32_16x16x32_bf16 v[84:87], v[172:175], v[204:207], v[84:87]
	v_mfma_f32_16x16x32_bf16 v[80:83], v[180:183], v[204:207], v[80:83]
	v_mfma_f32_16x16x32_bf16 v[68:71], v[172:175], v[212:215], v[68:71]
	v_mfma_f32_16x16x32_bf16 v[64:67], v[180:183], v[212:215], v[64:67]
	s_setprio 0
	s_barrier
	s_mov_b64 s[62:63], s[28:29]
	s_add_i32 s28, s58, s36
	s_mov_b32 m0, s28
	ds_read_b128 v[184:187], v155 offset:49152
	ds_read_b128 v[188:191], v155 offset:50176
	ds_read_b128 v[192:195], v155 offset:51200
	ds_read_b128 v[196:199], v155 offset:52224
	ds_read_b128 v[200:203], v155 offset:53248
	ds_read_b128 v[204:207], v155 offset:54272
	ds_read_b128 v[208:211], v155 offset:55296
	ds_read_b128 v[212:215], v155 offset:56320
	s_add_u32 s64, s24, 0x80
	s_addc_u32 s65, s25, 0
	global_load_lds_dwordx4 v130, s[64:65]
	s_add_i32 m0, s28, 0x2000
	s_add_u32 s24, s24, 0x160080
	s_addc_u32 s25, s25, 0
	s_add_i32 s28, s59, s36
	global_load_lds_dwordx4 v134, s[64:65]
	s_mov_b32 m0, s28
	s_nop 0
	global_load_lds_dwordx4 v130, s[24:25]
	s_add_i32 m0, s28, 0x2000
	s_nop 0
	global_load_lds_dwordx4 v134, s[24:25]
	s_mov_b32 m0, s42
	s_nop 0
	s_add_u32 s66, s62, 0xffea0080
	s_addc_u32 s67, s63, -1
	global_load_lds_dwordx4 v128, s[66:67]
	s_mov_b32 m0, s43
	s_nop 0
	global_load_lds_dwordx4 v132, s[66:67]
	s_waitcnt vmcnt(8)
	s_waitcnt lgkmcnt(0)
	s_barrier
	s_setprio 1
	s_waitcnt lgkmcnt(0)
	v_mfma_f32_16x16x32_bf16 v[60:63], v[144:147], v[184:187], v[60:63]
	v_mfma_f32_16x16x32_bf16 v[56:59], v[160:163], v[184:187], v[56:59]
	v_mfma_f32_16x16x32_bf16 v[44:47], v[144:147], v[192:195], v[44:47]
	v_mfma_f32_16x16x32_bf16 v[40:43], v[160:163], v[192:195], v[40:43]
	v_mfma_f32_16x16x32_bf16 v[28:31], v[144:147], v[200:203], v[28:31]
	v_mfma_f32_16x16x32_bf16 v[24:27], v[160:163], v[200:203], v[24:27]
	v_mfma_f32_16x16x32_bf16 v[12:15], v[144:147], v[208:211], v[12:15]
	v_mfma_f32_16x16x32_bf16 v[8:11], v[160:163], v[208:211], v[8:11]
	v_mfma_f32_16x16x32_bf16 v[60:63], v[156:159], v[188:191], v[60:63]
	v_mfma_f32_16x16x32_bf16 v[56:59], v[164:167], v[188:191], v[56:59]
	v_mfma_f32_16x16x32_bf16 v[44:47], v[156:159], v[196:199], v[44:47]
	v_mfma_f32_16x16x32_bf16 v[40:43], v[164:167], v[196:199], v[40:43]
	v_mfma_f32_16x16x32_bf16 v[28:31], v[156:159], v[204:207], v[28:31]
	v_mfma_f32_16x16x32_bf16 v[24:27], v[164:167], v[204:207], v[24:27]
	v_mfma_f32_16x16x32_bf16 v[12:15], v[156:159], v[212:215], v[12:15]
	v_mfma_f32_16x16x32_bf16 v[8:11], v[164:167], v[212:215], v[8:11]
	s_setprio 0
	s_setprio 1
	v_mfma_f32_16x16x32_bf16 v[52:55], v[168:171], v[184:187], v[52:55]
	v_mfma_f32_16x16x32_bf16 v[48:51], v[176:179], v[184:187], v[48:51]
	v_mfma_f32_16x16x32_bf16 v[36:39], v[168:171], v[192:195], v[36:39]
	v_mfma_f32_16x16x32_bf16 v[32:35], v[176:179], v[192:195], v[32:35]
	v_mfma_f32_16x16x32_bf16 v[20:23], v[168:171], v[200:203], v[20:23]
	v_mfma_f32_16x16x32_bf16 v[16:19], v[176:179], v[200:203], v[16:19]
	v_mfma_f32_16x16x32_bf16 v[4:7], v[168:171], v[208:211], v[4:7]
	v_mfma_f32_16x16x32_bf16 v[0:3], v[176:179], v[208:211], v[0:3]
	v_mfma_f32_16x16x32_bf16 v[52:55], v[172:175], v[188:191], v[52:55]
	v_mfma_f32_16x16x32_bf16 v[48:51], v[180:183], v[188:191], v[48:51]
	v_mfma_f32_16x16x32_bf16 v[36:39], v[172:175], v[196:199], v[36:39]
	v_mfma_f32_16x16x32_bf16 v[32:35], v[180:183], v[196:199], v[32:35]
	v_mfma_f32_16x16x32_bf16 v[20:23], v[172:175], v[204:207], v[20:23]
	v_mfma_f32_16x16x32_bf16 v[16:19], v[180:183], v[204:207], v[16:19]
	v_mfma_f32_16x16x32_bf16 v[4:7], v[172:175], v[212:215], v[4:7]
	v_mfma_f32_16x16x32_bf16 v[0:3], v[180:183], v[212:215], v[0:3]
	s_setprio 0
	s_barrier
	s_add_i32 s57, s57, 2
	s_add_u32 s22, s22, 0x100
	s_addc_u32 s23, s23, 0
	s_add_u32 s55, s55, 0x100
	s_addc_u32 s56, s56, 0
	s_cmpk_gt_u32 s57, 0x55
	s_cbranch_scc0 .LBB0_742
	s_and_b64 vcc, exec, s[12:13]
	s_cbranch_vccz .LBB0_745
	s_barrier

; __global__ void __launch_bounds__(512, 2) fwd_kernel(Params p) {
;     extern __shared__ __attribute__((aligned(16))) unsigned char lds[];
;     const int tid = threadIdx.x, lane = tid & 63, wave = tid >> 6;
;     const int G = gridDim.x, bid = blockIdx.x;
;     unsigned char* ws = p.ws; unsigned char* dob = (unsigned char*)p.out;
	.amdhsa_kernel _Z10fwd_kernel6Params
		.amdhsa_group_segment_fixed_size 0
		.amdhsa_private_segment_fixed_size 0
		.amdhsa_kernarg_size 424
		.amdhsa_user_sgpr_count 2
		.amdhsa_user_sgpr_dispatch_ptr 0
		.amdhsa_user_sgpr_queue_ptr 0
		.amdhsa_user_sgpr_kernarg_segment_ptr 1
		.amdhsa_user_sgpr_dispatch_id 0
		.amdhsa_user_sgpr_kernarg_preload_length 0
		.amdhsa_user_sgpr_kernarg_preload_offset 0
		.amdhsa_user_sgpr_private_segment_size 0
		.amdhsa_uses_dynamic_stack 0
		.amdhsa_enable_private_segment 0
		.amdhsa_system_sgpr_workgroup_id_x 1
		.amdhsa_system_sgpr_workgroup_id_y 0
		.amdhsa_system_sgpr_workgroup_id_z 0
		.amdhsa_system_sgpr_workgroup_info 0
		.amdhsa_system_vgpr_workitem_id 2
		.amdhsa_next_free_vgpr 256
		.amdhsa_next_free_sgpr 102
		.amdhsa_accum_offset 256
		.amdhsa_reserve_vcc 1
		.amdhsa_float_round_mode_32 0
		.amdhsa_float_round_mode_16_64 0
		.amdhsa_float_denorm_mode_32 3
		.amdhsa_float_denorm_mode_16_64 3
		.amdhsa_dx10_clamp 1
		.amdhsa_ieee_mode 1
		.amdhsa_fp16_overflow 0
		.amdhsa_tg_split 0
		.amdhsa_exception_fp_ieee_invalid_op 0
		.amdhsa_exception_fp_denorm_src 0
		.amdhsa_exception_fp_ieee_div_zero 0
		.amdhsa_exception_fp_ieee_overflow 0
		.amdhsa_exception_fp_ieee_underflow 0
		.amdhsa_exception_fp_ieee_inexact 0
		.amdhsa_exception_int_div_zero 0
	.end_amdhsa_kernel

; __global__ void __launch_bounds__(512, 2) fwd_kernel(Params p) {
;     extern __shared__ __attribute__((aligned(16))) unsigned char lds[];
;     const int tid = threadIdx.x, lane = tid & 63, wave = tid >> 6;
;     const int G = gridDim.x, bid = blockIdx.x;
;     unsigned char* ws = p.ws; unsigned char* dob = (unsigned char*)p.out;
amdhsa.kernels:
  - .agpr_count:     0
    .args:
      - .offset:         0
        .size:           168
        .value_kind:     by_value
      - .offset:         168
        .size:           4
        .value_kind:     hidden_block_count_x
      - .offset:         172
        .size:           4
        .value_kind:     hidden_block_count_y
      - .offset:         176
        .size:           4
        .value_kind:     hidden_block_count_z
      - .offset:         180
        .size:           2
        .value_kind:     hidden_group_size_x
      - .offset:         182
        .size:           2
        .value_kind:     hidden_group_size_y
      - .offset:         184
        .size:           2
        .value_kind:     hidden_group_size_z
      - .offset:         186
        .size:           2
        .value_kind:     hidden_remainder_x
      - .offset:         188
        .size:           2
        .value_kind:     hidden_remainder_y
      - .offset:         190
        .size:           2
        .value_kind:     hidden_remainder_z
      - .offset:         208
        .size:           8
        .value_kind:     hidden_global_offset_x
      - .offset:         216
        .size:           8
        .value_kind:     hidden_global_offset_y
      - .offset:         224
        .size:           8
        .value_kind:     hidden_global_offset_z
      - .offset:         232
        .size:           2
        .value_kind:     hidden_grid_dims
      - .offset:         256
        .size:           8
        .value_kind:     hidden_multigrid_sync_arg
      - .offset:         288
        .size:           4
        .value_kind:     hidden_dynamic_lds_size
    .group_segment_fixed_size: 0
    .kernarg_segment_align: 8
    .kernarg_segment_size: 424
    .language:       OpenCL C
    .language_version:
      - 2
      - 0
    .max_flat_workgroup_size: 512
    .name:           _Z10fwd_kernel6Params
    .private_segment_fixed_size: 0
    .sgpr_count:     108
    .sgpr_spill_count: 18
    .symbol:         _Z10fwd_kernel6Params.kd
    .uniform_work_group_size: 1
    .uses_dynamic_stack: false
    .vgpr_count:     256
    .vgpr_spill_count: 0
    .wavefront_size: 64
